# K-loops (in-proj, up, down): LDS-DMA target bases formed once per tile, 8 scalar ops per iteration removed
# baseline (speedup 1.0000x reference)
.LBB0_137:
	s_ashr_i32 s49, s48, 31
	s_lshl_b64 s[22:23], s[48:49], 20
	s_add_u32 s52, s26, s22
	s_addc_u32 s53, s27, s23
	s_and_b64 s[0:1], s[0:1], exec
	s_cselect_b32 s22, s53, s7
	s_cselect_b32 s23, s52, s6
	s_add_u32 s0, s12, 0x80080
	s_addc_u32 s1, s13, 0
	s_add_u32 s38, s6, 0x100
	v_mov_b32_e32 v2, 0
	s_addc_u32 s39, s7, 0
	s_mov_b32 s49, -2
	v_mov_b32_e32 v3, v2
	v_mov_b32_e32 v4, v2
	v_mov_b32_e32 v5, v2
	v_mov_b32_e32 v6, v2
	v_mov_b32_e32 v7, v2
	v_mov_b32_e32 v8, v2
	v_mov_b32_e32 v9, v2
	v_mov_b32_e32 v14, v2
	v_mov_b32_e32 v15, v2
	v_mov_b32_e32 v16, v2
	v_mov_b32_e32 v17, v2
	v_mov_b32_e32 v22, v2
	v_mov_b32_e32 v23, v2
	v_mov_b32_e32 v24, v2
	v_mov_b32_e32 v25, v2
	v_mov_b32_e32 v30, v2
	v_mov_b32_e32 v31, v2
	v_mov_b32_e32 v32, v2
	v_mov_b32_e32 v33, v2
	v_mov_b32_e32 v38, v2
	v_mov_b32_e32 v39, v2
	v_mov_b32_e32 v40, v2
	v_mov_b32_e32 v41, v2
	v_mov_b32_e32 v46, v2
	v_mov_b32_e32 v47, v2
	v_mov_b32_e32 v48, v2
	v_mov_b32_e32 v49, v2
	v_mov_b32_e32 v54, v2
	v_mov_b32_e32 v55, v2
	v_mov_b32_e32 v56, v2
	v_mov_b32_e32 v57, v2
	v_mov_b32_e32 v10, v2
	v_mov_b32_e32 v11, v2
	v_mov_b32_e32 v12, v2
	v_mov_b32_e32 v13, v2
	v_mov_b32_e32 v18, v2
	v_mov_b32_e32 v19, v2
	v_mov_b32_e32 v20, v2
	v_mov_b32_e32 v21, v2
	v_mov_b32_e32 v26, v2
	v_mov_b32_e32 v27, v2
	v_mov_b32_e32 v28, v2
	v_mov_b32_e32 v29, v2
	v_mov_b32_e32 v34, v2
	v_mov_b32_e32 v35, v2
	v_mov_b32_e32 v36, v2
	v_mov_b32_e32 v37, v2
	v_mov_b32_e32 v42, v2
	v_mov_b32_e32 v43, v2
	v_mov_b32_e32 v44, v2
	v_mov_b32_e32 v45, v2
	v_mov_b32_e32 v50, v2
	v_mov_b32_e32 v51, v2
	v_mov_b32_e32 v52, v2
	v_mov_b32_e32 v53, v2
	v_mov_b32_e32 v58, v2
	v_mov_b32_e32 v59, v2
	v_mov_b32_e32 v60, v2
	v_mov_b32_e32 v61, v2
	v_mov_b32_e32 v62, v2
	v_mov_b32_e32 v63, v2
	v_mov_b32_e32 v64, v2
	v_mov_b32_e32 v65, v2
	v_mov_b32_e32 v66, v2
	v_mov_b32_e32 v67, v2
	v_mov_b32_e32 v68, v2
	v_mov_b32_e32 v69, v2
	v_mov_b32_e32 v70, v2
	v_mov_b32_e32 v71, v2
	v_mov_b32_e32 v72, v2
	v_mov_b32_e32 v73, v2
	v_mov_b32_e32 v78, v2
	v_mov_b32_e32 v79, v2
	v_mov_b32_e32 v80, v2
	v_mov_b32_e32 v81, v2
	v_mov_b32_e32 v86, v2
	v_mov_b32_e32 v87, v2
	v_mov_b32_e32 v88, v2
	v_mov_b32_e32 v89, v2
	v_mov_b32_e32 v94, v2
	v_mov_b32_e32 v95, v2
	v_mov_b32_e32 v96, v2
	v_mov_b32_e32 v97, v2
	v_mov_b32_e32 v102, v2
	v_mov_b32_e32 v103, v2
	v_mov_b32_e32 v104, v2
	v_mov_b32_e32 v105, v2
	v_mov_b32_e32 v110, v2
	v_mov_b32_e32 v111, v2
	v_mov_b32_e32 v112, v2
	v_mov_b32_e32 v113, v2
	v_mov_b32_e32 v118, v2
	v_mov_b32_e32 v119, v2
	v_mov_b32_e32 v120, v2
	v_mov_b32_e32 v121, v2
	v_mov_b32_e32 v74, v2
	v_mov_b32_e32 v75, v2
	v_mov_b32_e32 v76, v2
	v_mov_b32_e32 v77, v2
	v_mov_b32_e32 v82, v2
	v_mov_b32_e32 v83, v2
	v_mov_b32_e32 v84, v2
	v_mov_b32_e32 v85, v2
	v_mov_b32_e32 v90, v2
	v_mov_b32_e32 v91, v2
	v_mov_b32_e32 v92, v2
	v_mov_b32_e32 v93, v2
	v_mov_b32_e32 v98, v2
	v_mov_b32_e32 v99, v2
	v_mov_b32_e32 v100, v2
	v_mov_b32_e32 v101, v2
	v_mov_b32_e32 v106, v2
	v_mov_b32_e32 v107, v2
	v_mov_b32_e32 v108, v2
	v_mov_b32_e32 v109, v2
	v_mov_b32_e32 v114, v2
	v_mov_b32_e32 v115, v2
	v_mov_b32_e32 v116, v2
	v_mov_b32_e32 v117, v2
	v_mov_b32_e32 v122, v2
	v_mov_b32_e32 v123, v2
	v_mov_b32_e32 v124, v2
	v_mov_b32_e32 v125, v2
	v_mov_b32_e32 v126, v2
	v_mov_b32_e32 v127, v2
	v_mov_b32_e32 v128, v2
	v_mov_b32_e32 v129, v2
	v_add_u32_e32 v224, 0x10000, v149
	v_add_u32_e32 v225, 0x14000, v149
	v_add_u32_e32 v226, 0x18000, v149
	v_add_u32_e32 v227, 0x1c000, v149
	s_add_i32 s84, s30, 0x10000
	s_add_i32 s85, s30, 0x14000
	s_add_i32 s87, s30, 0x18000
	s_add_i32 s88, s30, 0x1c000
.LBB0_138:
	s_add_u32 s6, s0, 0xfff80080
	s_addc_u32 s7, s1, -1
	ds_read_b128 v[130:133], v224
	ds_read_b128 v[134:137], v224 offset:1024
	ds_read_b128 v[138:141], v224 offset:2048
	ds_read_b128 v[142:145], v224 offset:3072
	s_cmp_eq_u32 s49, 28
	s_cselect_b32 s13, s51, s7
	s_cselect_b32 s12, s50, s6
	s_cselect_b32 s7, s22, s39
	s_cselect_b32 s6, s23, s38
	s_add_i32 m0, s31, 0xc000
	ds_read_b128 v[152:155], v174
	ds_read_b128 v[166:169], v174 offset:1024
	ds_read_b128 v[170:173], v174 offset:2048
	ds_read_b128 v[176:179], v174 offset:3072
	ds_read_b128 v[180:183], v174 offset:4096
	ds_read_b128 v[184:187], v174 offset:5120
	ds_read_b128 v[188:191], v174 offset:6144
	global_load_lds_dwordx4 v162, s[0:1]
	s_add_i32 m0, s31, 0xe000
	ds_read_b128 v[192:195], v174 offset:7168
	global_load_lds_dwordx4 v164, s[0:1]
	s_waitcnt lgkmcnt(8)
	s_barrier
	s_waitcnt lgkmcnt(7)
	v_mfma_f32_16x16x32_bf16 v[126:129], v[130:133], v[152:155], v[126:129]
	v_mfma_f32_16x16x32_bf16 v[122:125], v[138:141], v[152:155], v[122:125]
	s_waitcnt lgkmcnt(5)
	v_mfma_f32_16x16x32_bf16 v[114:117], v[130:133], v[170:173], v[114:117]
	v_mfma_f32_16x16x32_bf16 v[106:109], v[138:141], v[170:173], v[106:109]
	s_waitcnt lgkmcnt(3)
	v_mfma_f32_16x16x32_bf16 v[98:101], v[130:133], v[180:183], v[98:101]
	v_mfma_f32_16x16x32_bf16 v[90:93], v[138:141], v[180:183], v[90:93]
	s_waitcnt lgkmcnt(1)
	v_mfma_f32_16x16x32_bf16 v[82:85], v[130:133], v[188:191], v[82:85]
	v_mfma_f32_16x16x32_bf16 v[74:77], v[138:141], v[188:191], v[74:77]
	v_mfma_f32_16x16x32_bf16 v[126:129], v[134:137], v[166:169], v[126:129]
	v_mfma_f32_16x16x32_bf16 v[122:125], v[142:145], v[166:169], v[122:125]
	v_mfma_f32_16x16x32_bf16 v[114:117], v[134:137], v[176:179], v[114:117]
	v_mfma_f32_16x16x32_bf16 v[106:109], v[142:145], v[176:179], v[106:109]
	v_mfma_f32_16x16x32_bf16 v[98:101], v[134:137], v[184:187], v[98:101]
	v_mfma_f32_16x16x32_bf16 v[90:93], v[142:145], v[184:187], v[90:93]
	s_waitcnt lgkmcnt(0)
	v_mfma_f32_16x16x32_bf16 v[82:85], v[134:137], v[192:195], v[82:85]
	v_mfma_f32_16x16x32_bf16 v[74:77], v[142:145], v[192:195], v[74:77]
	s_barrier
	s_mov_b32 m0, s84
	ds_read_b128 v[196:199], v225
	ds_read_b128 v[200:203], v225 offset:1024
	ds_read_b128 v[204:207], v225 offset:2048
	global_load_lds_dwordx4 v158, s[6:7]
	s_add_i32 m0, s84, 0x2000
	ds_read_b128 v[216:219], v225 offset:3072
	global_load_lds_dwordx4 v146, s[6:7]
	s_barrier
	s_waitcnt lgkmcnt(3)
	v_mfma_f32_16x16x32_bf16 v[118:121], v[196:199], v[152:155], v[118:121]
	s_waitcnt lgkmcnt(1)
	v_mfma_f32_16x16x32_bf16 v[110:113], v[204:207], v[152:155], v[110:113]
	v_mfma_f32_16x16x32_bf16 v[102:105], v[196:199], v[170:173], v[102:105]
	v_mfma_f32_16x16x32_bf16 v[94:97], v[204:207], v[170:173], v[94:97]
	v_mfma_f32_16x16x32_bf16 v[86:89], v[196:199], v[180:183], v[86:89]
	v_mfma_f32_16x16x32_bf16 v[78:81], v[204:207], v[180:183], v[78:81]
	v_mfma_f32_16x16x32_bf16 v[70:73], v[196:199], v[188:191], v[70:73]
	v_mfma_f32_16x16x32_bf16 v[66:69], v[204:207], v[188:191], v[66:69]
	v_mfma_f32_16x16x32_bf16 v[118:121], v[200:203], v[166:169], v[118:121]
	s_waitcnt lgkmcnt(0)
	v_mfma_f32_16x16x32_bf16 v[110:113], v[216:219], v[166:169], v[110:113]
	v_mfma_f32_16x16x32_bf16 v[102:105], v[200:203], v[176:179], v[102:105]
	v_mfma_f32_16x16x32_bf16 v[94:97], v[216:219], v[176:179], v[94:97]
	v_mfma_f32_16x16x32_bf16 v[86:89], v[200:203], v[184:187], v[86:89]
	v_mfma_f32_16x16x32_bf16 v[78:81], v[216:219], v[184:187], v[78:81]
	v_mfma_f32_16x16x32_bf16 v[70:73], v[200:203], v[192:195], v[70:73]
	v_mfma_f32_16x16x32_bf16 v[66:69], v[216:219], v[192:195], v[66:69]
	s_mov_b32 m0, s31
	s_add_u32 s98, s12, 0x80
	s_addc_u32 s99, s13, 0
	s_barrier
	ds_read_b128 v[152:155], v174 offset:16384
	ds_read_b128 v[166:169], v174 offset:17408
	ds_read_b128 v[170:173], v174 offset:18432
	ds_read_b128 v[176:179], v174 offset:19456
	ds_read_b128 v[180:183], v174 offset:20480
	ds_read_b128 v[184:187], v174 offset:21504
	ds_read_b128 v[188:191], v174 offset:22528
	global_load_lds_dwordx4 v160, s[12:13]
	s_mov_b32 m0, s40
	ds_read_b128 v[192:195], v174 offset:23552
	global_load_lds_dwordx4 v156, s[12:13]
	s_barrier
	s_waitcnt lgkmcnt(7)
	v_mfma_f32_16x16x32_bf16 v[62:65], v[130:133], v[152:155], v[62:65]
	v_mfma_f32_16x16x32_bf16 v[58:61], v[138:141], v[152:155], v[58:61]
	s_waitcnt lgkmcnt(5)
	v_mfma_f32_16x16x32_bf16 v[50:53], v[130:133], v[170:173], v[50:53]
	v_mfma_f32_16x16x32_bf16 v[42:45], v[138:141], v[170:173], v[42:45]
	s_waitcnt lgkmcnt(3)
	v_mfma_f32_16x16x32_bf16 v[34:37], v[130:133], v[180:183], v[34:37]
	v_mfma_f32_16x16x32_bf16 v[26:29], v[138:141], v[180:183], v[26:29]
	s_waitcnt lgkmcnt(1)
	v_mfma_f32_16x16x32_bf16 v[18:21], v[130:133], v[188:191], v[18:21]
	v_mfma_f32_16x16x32_bf16 v[10:13], v[138:141], v[188:191], v[10:13]
	v_mfma_f32_16x16x32_bf16 v[62:65], v[134:137], v[166:169], v[62:65]
	v_mfma_f32_16x16x32_bf16 v[58:61], v[142:145], v[166:169], v[58:61]
	v_mfma_f32_16x16x32_bf16 v[50:53], v[134:137], v[176:179], v[50:53]
	v_mfma_f32_16x16x32_bf16 v[42:45], v[142:145], v[176:179], v[42:45]
	v_mfma_f32_16x16x32_bf16 v[34:37], v[134:137], v[184:187], v[34:37]
	v_mfma_f32_16x16x32_bf16 v[26:29], v[142:145], v[184:187], v[26:29]
	s_waitcnt lgkmcnt(0)
	v_mfma_f32_16x16x32_bf16 v[18:21], v[134:137], v[192:195], v[18:21]
	v_mfma_f32_16x16x32_bf16 v[10:13], v[142:145], v[192:195], v[10:13]
	s_barrier
	s_mov_b32 m0, s85
	s_add_u32 s76, s6, 0x80000
	s_addc_u32 s77, s7, 0
	global_load_lds_dwordx4 v158, s[76:77]
	s_add_i32 m0, s85, 0x2000
	s_nop 0
	global_load_lds_dwordx4 v146, s[76:77]
	s_waitcnt vmcnt(6)
	s_barrier
	v_mfma_f32_16x16x32_bf16 v[54:57], v[196:199], v[152:155], v[54:57]
	v_mfma_f32_16x16x32_bf16 v[46:49], v[204:207], v[152:155], v[46:49]
	v_mfma_f32_16x16x32_bf16 v[38:41], v[196:199], v[170:173], v[38:41]
	v_mfma_f32_16x16x32_bf16 v[30:33], v[204:207], v[170:173], v[30:33]
	v_mfma_f32_16x16x32_bf16 v[22:25], v[196:199], v[180:183], v[22:25]
	v_mfma_f32_16x16x32_bf16 v[14:17], v[204:207], v[180:183], v[14:17]
	v_mfma_f32_16x16x32_bf16 v[6:9], v[196:199], v[188:191], v[6:9]
	v_mfma_f32_16x16x32_bf16 v[2:5], v[204:207], v[188:191], v[2:5]
	v_mfma_f32_16x16x32_bf16 v[54:57], v[200:203], v[166:169], v[54:57]
	v_mfma_f32_16x16x32_bf16 v[46:49], v[216:219], v[166:169], v[46:49]
	v_mfma_f32_16x16x32_bf16 v[38:41], v[200:203], v[176:179], v[38:41]
	v_mfma_f32_16x16x32_bf16 v[30:33], v[216:219], v[176:179], v[30:33]
	v_mfma_f32_16x16x32_bf16 v[22:25], v[200:203], v[184:187], v[22:25]
	v_mfma_f32_16x16x32_bf16 v[14:17], v[216:219], v[184:187], v[14:17]
	v_mfma_f32_16x16x32_bf16 v[6:9], v[200:203], v[192:195], v[6:9]
	v_mfma_f32_16x16x32_bf16 v[2:5], v[216:219], v[192:195], v[2:5]
	s_barrier
	ds_read_b128 v[130:133], v226
	ds_read_b128 v[134:137], v226 offset:1024
	ds_read_b128 v[138:141], v226 offset:2048
	ds_read_b128 v[142:145], v226 offset:3072
	s_add_u32 s12, s12, 0x80000
	s_addc_u32 s13, s13, 0
	s_mov_b32 m0, s41
	ds_read_b128 v[152:155], v174 offset:32768
	ds_read_b128 v[166:169], v174 offset:33792
	ds_read_b128 v[170:173], v174 offset:34816
	ds_read_b128 v[176:179], v174 offset:35840
	ds_read_b128 v[180:183], v174 offset:36864
	ds_read_b128 v[184:187], v174 offset:37888
	ds_read_b128 v[188:191], v174 offset:38912
	global_load_lds_dwordx4 v160, s[12:13]
	s_mov_b32 m0, s60
	ds_read_b128 v[192:195], v174 offset:39936
	global_load_lds_dwordx4 v156, s[12:13]
	s_waitcnt lgkmcnt(8)
	s_barrier
	s_waitcnt lgkmcnt(7)
	v_mfma_f32_16x16x32_bf16 v[126:129], v[130:133], v[152:155], v[126:129]
	v_mfma_f32_16x16x32_bf16 v[122:125], v[138:141], v[152:155], v[122:125]
	s_waitcnt lgkmcnt(5)
	v_mfma_f32_16x16x32_bf16 v[114:117], v[130:133], v[170:173], v[114:117]
	v_mfma_f32_16x16x32_bf16 v[106:109], v[138:141], v[170:173], v[106:109]
	s_waitcnt lgkmcnt(3)
	v_mfma_f32_16x16x32_bf16 v[98:101], v[130:133], v[180:183], v[98:101]
	v_mfma_f32_16x16x32_bf16 v[90:93], v[138:141], v[180:183], v[90:93]
	s_waitcnt lgkmcnt(1)
	v_mfma_f32_16x16x32_bf16 v[82:85], v[130:133], v[188:191], v[82:85]
	v_mfma_f32_16x16x32_bf16 v[74:77], v[138:141], v[188:191], v[74:77]
	v_mfma_f32_16x16x32_bf16 v[126:129], v[134:137], v[166:169], v[126:129]
	v_mfma_f32_16x16x32_bf16 v[122:125], v[142:145], v[166:169], v[122:125]
	v_mfma_f32_16x16x32_bf16 v[114:117], v[134:137], v[176:179], v[114:117]
	v_mfma_f32_16x16x32_bf16 v[106:109], v[142:145], v[176:179], v[106:109]
	v_mfma_f32_16x16x32_bf16 v[98:101], v[134:137], v[184:187], v[98:101]
	v_mfma_f32_16x16x32_bf16 v[90:93], v[142:145], v[184:187], v[90:93]
	s_waitcnt lgkmcnt(0)
	v_mfma_f32_16x16x32_bf16 v[82:85], v[134:137], v[192:195], v[82:85]
	v_mfma_f32_16x16x32_bf16 v[74:77], v[142:145], v[192:195], v[74:77]
	s_barrier
	s_add_u32 s100, s6, 0x80
	s_addc_u32 s101, s7, 0
	s_mov_b32 m0, s87
	ds_read_b128 v[196:199], v227
	ds_read_b128 v[200:203], v227 offset:1024
	ds_read_b128 v[204:207], v227 offset:2048
	global_load_lds_dwordx4 v158, s[100:101]
	s_add_i32 m0, s87, 0x2000
	ds_read_b128 v[216:219], v227 offset:3072
	global_load_lds_dwordx4 v146, s[100:101]
	s_barrier
	s_waitcnt lgkmcnt(3)
	v_mfma_f32_16x16x32_bf16 v[118:121], v[196:199], v[152:155], v[118:121]
	s_waitcnt lgkmcnt(1)
	v_mfma_f32_16x16x32_bf16 v[110:113], v[204:207], v[152:155], v[110:113]
	v_mfma_f32_16x16x32_bf16 v[102:105], v[196:199], v[170:173], v[102:105]
	v_mfma_f32_16x16x32_bf16 v[94:97], v[204:207], v[170:173], v[94:97]
	v_mfma_f32_16x16x32_bf16 v[86:89], v[196:199], v[180:183], v[86:89]
	v_mfma_f32_16x16x32_bf16 v[78:81], v[204:207], v[180:183], v[78:81]
	v_mfma_f32_16x16x32_bf16 v[70:73], v[196:199], v[188:191], v[70:73]
	v_mfma_f32_16x16x32_bf16 v[66:69], v[204:207], v[188:191], v[66:69]
	v_mfma_f32_16x16x32_bf16 v[118:121], v[200:203], v[166:169], v[118:121]
	s_waitcnt lgkmcnt(0)
	v_mfma_f32_16x16x32_bf16 v[110:113], v[216:219], v[166:169], v[110:113]
	v_mfma_f32_16x16x32_bf16 v[102:105], v[200:203], v[176:179], v[102:105]
	v_mfma_f32_16x16x32_bf16 v[94:97], v[216:219], v[176:179], v[94:97]
	v_mfma_f32_16x16x32_bf16 v[86:89], v[200:203], v[184:187], v[86:89]
	v_mfma_f32_16x16x32_bf16 v[78:81], v[216:219], v[184:187], v[78:81]
	v_mfma_f32_16x16x32_bf16 v[70:73], v[200:203], v[192:195], v[70:73]
	v_mfma_f32_16x16x32_bf16 v[66:69], v[216:219], v[192:195], v[66:69]
	s_mov_b32 m0, s64
	s_barrier
	ds_read_b128 v[152:155], v174 offset:49152
	ds_read_b128 v[166:169], v174 offset:50176
	ds_read_b128 v[170:173], v174 offset:51200
	ds_read_b128 v[176:179], v174 offset:52224
	ds_read_b128 v[180:183], v174 offset:53248
	ds_read_b128 v[184:187], v174 offset:54272
	ds_read_b128 v[188:191], v174 offset:55296
	global_load_lds_dwordx4 v160, s[98:99]
	s_mov_b32 m0, s65
	ds_read_b128 v[192:195], v174 offset:56320
	global_load_lds_dwordx4 v156, s[98:99]
	s_barrier
	s_waitcnt lgkmcnt(7)
	v_mfma_f32_16x16x32_bf16 v[62:65], v[130:133], v[152:155], v[62:65]
	v_mfma_f32_16x16x32_bf16 v[58:61], v[138:141], v[152:155], v[58:61]
	s_waitcnt lgkmcnt(5)
	v_mfma_f32_16x16x32_bf16 v[50:53], v[130:133], v[170:173], v[50:53]
	v_mfma_f32_16x16x32_bf16 v[42:45], v[138:141], v[170:173], v[42:45]
	s_waitcnt lgkmcnt(3)
	v_mfma_f32_16x16x32_bf16 v[34:37], v[130:133], v[180:183], v[34:37]
	v_mfma_f32_16x16x32_bf16 v[26:29], v[138:141], v[180:183], v[26:29]
	s_waitcnt lgkmcnt(1)
	v_mfma_f32_16x16x32_bf16 v[18:21], v[130:133], v[188:191], v[18:21]
	v_mfma_f32_16x16x32_bf16 v[10:13], v[138:141], v[188:191], v[10:13]
	v_mfma_f32_16x16x32_bf16 v[62:65], v[134:137], v[166:169], v[62:65]
	v_mfma_f32_16x16x32_bf16 v[58:61], v[142:145], v[166:169], v[58:61]
	v_mfma_f32_16x16x32_bf16 v[50:53], v[134:137], v[176:179], v[50:53]
	v_mfma_f32_16x16x32_bf16 v[42:45], v[142:145], v[176:179], v[42:45]
	v_mfma_f32_16x16x32_bf16 v[34:37], v[134:137], v[184:187], v[34:37]
	v_mfma_f32_16x16x32_bf16 v[26:29], v[142:145], v[184:187], v[26:29]
	s_waitcnt lgkmcnt(0)
	v_mfma_f32_16x16x32_bf16 v[18:21], v[134:137], v[192:195], v[18:21]
	v_mfma_f32_16x16x32_bf16 v[10:13], v[142:145], v[192:195], v[10:13]
	s_barrier
	s_mov_b32 m0, s88
	s_add_u32 s6, s6, 0x80080
	s_addc_u32 s7, s7, 0
	global_load_lds_dwordx4 v158, s[6:7]
	s_add_i32 m0, s88, 0x2000
	s_nop 0
	global_load_lds_dwordx4 v146, s[6:7]
	s_waitcnt vmcnt(6)
	s_barrier
	v_mfma_f32_16x16x32_bf16 v[54:57], v[196:199], v[152:155], v[54:57]
	v_mfma_f32_16x16x32_bf16 v[46:49], v[204:207], v[152:155], v[46:49]
	v_mfma_f32_16x16x32_bf16 v[38:41], v[196:199], v[170:173], v[38:41]
	v_mfma_f32_16x16x32_bf16 v[30:33], v[204:207], v[170:173], v[30:33]
	v_mfma_f32_16x16x32_bf16 v[22:25], v[196:199], v[180:183], v[22:25]
	v_mfma_f32_16x16x32_bf16 v[14:17], v[204:207], v[180:183], v[14:17]
	v_mfma_f32_16x16x32_bf16 v[6:9], v[196:199], v[188:191], v[6:9]
	v_mfma_f32_16x16x32_bf16 v[2:5], v[204:207], v[188:191], v[2:5]
	v_mfma_f32_16x16x32_bf16 v[54:57], v[200:203], v[166:169], v[54:57]
	v_mfma_f32_16x16x32_bf16 v[46:49], v[216:219], v[166:169], v[46:49]
	v_mfma_f32_16x16x32_bf16 v[38:41], v[200:203], v[176:179], v[38:41]
	v_mfma_f32_16x16x32_bf16 v[30:33], v[216:219], v[176:179], v[30:33]
	v_mfma_f32_16x16x32_bf16 v[22:25], v[200:203], v[184:187], v[22:25]
	v_mfma_f32_16x16x32_bf16 v[14:17], v[216:219], v[184:187], v[14:17]
	v_mfma_f32_16x16x32_bf16 v[6:9], v[200:203], v[192:195], v[6:9]
	v_mfma_f32_16x16x32_bf16 v[2:5], v[216:219], v[192:195], v[2:5]
	s_add_i32 s49, s49, 2
	s_add_u32 s0, s0, 0x100
	s_addc_u32 s1, s1, 0
	s_add_u32 s38, s38, 0x100
	s_addc_u32 s39, s39, 0
	s_cmp_gt_u32 s49, 29
	s_barrier
	s_cbranch_scc0 .LBB0_138
	v_mov_b32_e32 v0, v148
	s_cmp_gt_i32 s69, 15
	v_and_b32_e32 v176, 15, v0
	v_bfe_u32 v175, v0, 4, 2
	s_mov_b64 s[0:1], -1
	s_cbranch_scc0 .LBB0_157
	s_cmp_gt_u32 s69, 23
	s_cbranch_scc0 .LBB0_154
	s_cmp_gt_u32 s69, 31
	s_cbranch_scc0 .LBB0_151
	s_cmp_gt_u32 s69, 39
	s_cbranch_scc0 .LBB0_148
	v_mul_f32_e32 v0, 0xbfb8aa3b, v126
	v_exp_f32_e32 v131, v0
	s_lshr_b32 s0, s75, 3
	s_mulk_i32 s0, 0x880
	s_lshl_b32 s1, s75, 8
	v_add_f32_e32 v131, 1.0, v131
	v_rcp_f32_e32 v132, v131
	v_mul_f32_e32 v131, 0xbfb8aa3b, v122
	v_mul_f32_e32 v133, 0xbfb8aa3b, v127
	v_mul_f32_e32 v134, 0xbfb8aa3b, v123
	v_mul_f32_e32 v135, 0xbfb8aa3b, v128
	v_mul_f32_e32 v136, 0xbfb8aa3b, v124
	v_mul_f32_e32 v137, 0xbfb8aa3b, v129
	v_mul_f32_e32 v138, 0xbfb8aa3b, v125
	v_mul_f32_e32 v139, 0xbfb8aa3b, v118
	v_mul_f32_e32 v140, 0xbfb8aa3b, v110
	v_mul_f32_e32 v141, 0xbfb8aa3b, v119
	v_mul_f32_e32 v142, 0xbfb8aa3b, v111
	v_mul_f32_e32 v143, 0xbfb8aa3b, v120
	v_mul_f32_e32 v152, 0xbfb8aa3b, v112
	v_mul_f32_e32 v153, 0xbfb8aa3b, v121
	v_mul_f32_e32 v154, 0xbfb8aa3b, v113
	v_mul_f32_e32 v155, 0xbfb8aa3b, v114
	v_mul_f32_e32 v177, 0xbfb8aa3b, v106
	v_mul_f32_e32 v178, 0xbfb8aa3b, v115
	v_mul_f32_e32 v179, 0xbfb8aa3b, v107
	v_mul_f32_e32 v180, 0xbfb8aa3b, v116
	v_mul_f32_e32 v181, 0xbfb8aa3b, v108
	v_mul_f32_e32 v182, 0xbfb8aa3b, v117
	v_mul_f32_e32 v183, 0xbfb8aa3b, v109
	v_mul_f32_e32 v184, 0xbfb8aa3b, v102
	v_mul_f32_e32 v185, 0xbfb8aa3b, v94
	v_mul_f32_e32 v186, 0xbfb8aa3b, v103
	v_mul_f32_e32 v187, 0xbfb8aa3b, v95
	v_mul_f32_e32 v188, 0xbfb8aa3b, v104
	v_mul_f32_e32 v189, 0xbfb8aa3b, v96
	v_mul_f32_e32 v190, 0xbfb8aa3b, v105
	v_mul_f32_e32 v191, 0xbfb8aa3b, v97
	v_mul_f32_e32 v192, 0xbfb8aa3b, v98
	v_mul_f32_e32 v193, 0xbfb8aa3b, v90
	v_mul_f32_e32 v194, 0xbfb8aa3b, v99
	v_mul_f32_e32 v195, 0xbfb8aa3b, v91
	v_mul_f32_e32 v196, 0xbfb8aa3b, v100
	v_mul_f32_e32 v197, 0xbfb8aa3b, v92
	v_mul_f32_e32 v198, 0xbfb8aa3b, v101
	v_mul_f32_e32 v199, 0xbfb8aa3b, v93
	v_mul_f32_e32 v200, 0xbfb8aa3b, v86
	v_mul_f32_e32 v201, 0xbfb8aa3b, v78
	v_mul_f32_e32 v202, 0xbfb8aa3b, v87
	v_mul_f32_e32 v203, 0xbfb8aa3b, v79
	v_mul_f32_e32 v204, 0xbfb8aa3b, v88
	v_mul_f32_e32 v205, 0xbfb8aa3b, v80
	v_mul_f32_e32 v206, 0xbfb8aa3b, v89
	v_mul_f32_e32 v207, 0xbfb8aa3b, v81
	v_mul_f32_e32 v208, 0xbfb8aa3b, v82
	v_mul_f32_e32 v209, 0xbfb8aa3b, v74
	v_mul_f32_e32 v215, 0xbfb8aa3b, v83
	v_mul_f32_e32 v216, 0xbfb8aa3b, v75
	v_mul_f32_e32 v217, 0xbfb8aa3b, v84
	v_mul_f32_e32 v218, 0xbfb8aa3b, v76
	v_mul_f32_e32 v219, 0xbfb8aa3b, v85
	v_mul_f32_e32 v220, 0xbfb8aa3b, v77
	v_mul_f32_e32 v221, 0xbfb8aa3b, v70
	v_mul_f32_e32 v222, 0xbfb8aa3b, v66
	v_mul_f32_e32 v223, 0xbfb8aa3b, v71
	v_mul_f32_e32 v224, 0xbfb8aa3b, v67
	v_mul_f32_e32 v225, 0xbfb8aa3b, v72
	v_mul_f32_e32 v226, 0xbfb8aa3b, v68
	v_mul_f32_e32 v227, 0xbfb8aa3b, v73
	v_mul_f32_e32 v228, 0xbfb8aa3b, v69
	v_mul_f32_e32 v229, 0xbfb8aa3b, v62
	v_mul_f32_e32 v230, 0xbfb8aa3b, v58
	v_mul_f32_e32 v231, 0xbfb8aa3b, v63
	v_mul_f32_e32 v232, 0xbfb8aa3b, v59
	v_mul_f32_e32 v233, 0xbfb8aa3b, v64
	v_mul_f32_e32 v234, 0xbfb8aa3b, v60
	v_mul_f32_e32 v235, 0xbfb8aa3b, v65
	v_mul_f32_e32 v236, 0xbfb8aa3b, v61
	v_mul_f32_e32 v237, 0xbfb8aa3b, v54
	v_mul_f32_e32 v238, 0xbfb8aa3b, v46
	v_mul_f32_e32 v239, 0xbfb8aa3b, v55
	s_and_b32 s1, s1, 0x700
	s_add_i32 s0, s0, s66
	v_exp_f32_e32 v173, v131
	v_exp_f32_e32 v133, v133
	v_exp_f32_e32 v172, v134
	v_exp_f32_e32 v171, v135
	v_exp_f32_e32 v170, v136
	v_exp_f32_e32 v169, v137
	v_exp_f32_e32 v131, v138
	v_exp_f32_e32 v168, v139
	v_exp_f32_e32 v167, v140
	v_exp_f32_e32 v166, v141
	v_exp_f32_e32 v145, v142
	v_exp_f32_e32 v144, v143
	v_exp_f32_e32 v143, v152
	v_exp_f32_e32 v142, v153
	v_exp_f32_e32 v141, v154
	v_exp_f32_e32 v140, v155
	v_exp_f32_e32 v139, v177
	v_exp_f32_e32 v138, v178
	v_exp_f32_e32 v213, v179
	v_exp_f32_e32 v155, v180
	v_exp_f32_e32 v154, v181
	v_exp_f32_e32 v153, v182
	v_exp_f32_e32 v152, v183
	v_exp_f32_e32 v212, v184
	v_exp_f32_e32 v211, v185
	v_exp_f32_e32 v252, v186
	v_exp_f32_e32 v251, v187
	v_exp_f32_e32 v250, v188
	v_exp_f32_e32 v249, v189
	v_exp_f32_e32 v248, v190
	v_exp_f32_e32 v247, v191
	v_exp_f32_e32 v246, v192
	v_exp_f32_e32 v245, v193
	v_exp_f32_e32 v244, v194
	v_exp_f32_e32 v243, v195
	v_exp_f32_e32 v242, v196
	v_exp_f32_e32 v241, v197
	v_exp_f32_e32 v184, v198
	v_exp_f32_e32 v177, v199
	v_exp_f32_e32 v198, v200
	v_exp_f32_e32 v199, v201
	v_exp_f32_e32 v197, v202
	v_exp_f32_e32 v196, v203
	v_exp_f32_e32 v195, v204
	v_exp_f32_e32 v194, v205
	v_exp_f32_e32 v193, v206
	v_exp_f32_e32 v192, v207
	v_exp_f32_e32 v191, v208
	v_exp_f32_e32 v190, v209
	v_exp_f32_e32 v189, v215
	v_exp_f32_e32 v188, v216
	v_exp_f32_e32 v187, v217
	v_exp_f32_e32 v186, v218
	v_exp_f32_e32 v185, v219
	v_exp_f32_e32 v201, v220
	v_exp_f32_e32 v200, v221
	v_exp_f32_e32 v221, v222
	v_exp_f32_e32 v220, v223
	v_exp_f32_e32 v219, v224
	v_exp_f32_e32 v218, v225
	v_exp_f32_e32 v217, v226
	v_exp_f32_e32 v216, v227
	v_exp_f32_e32 v215, v228
	v_exp_f32_e32 v209, v229
	v_exp_f32_e32 v208, v230
	v_exp_f32_e32 v207, v231
	v_exp_f32_e32 v206, v232
	v_exp_f32_e32 v205, v233
	v_exp_f32_e32 v204, v234
	v_exp_f32_e32 v203, v235
	v_exp_f32_e32 v202, v236
	v_exp_f32_e32 v223, v237
	v_exp_f32_e32 v222, v238
	v_exp_f32_e32 v238, v239
	s_add_i32 s0, s0, s1
	s_lshl_b32 s1, s69, 8
	v_lshl_or_b32 v130, v175, 3, s1
	s_cmp_gt_u32 s69, 47
	v_or_b32_e32 v240, s0, v176
	v_or_b32_e32 v130, s61, v130
	s_mov_b64 s[0:1], -1
	v_mul_f32_e32 v237, 0xbfb8aa3b, v47
	v_mul_f32_e32 v236, 0xbfb8aa3b, v56
	v_mul_f32_e32 v235, 0xbfb8aa3b, v48
	v_mul_f32_e32 v234, 0xbfb8aa3b, v57
	v_mul_f32_e32 v233, 0xbfb8aa3b, v49
	v_mul_f32_e32 v232, 0xbfb8aa3b, v50
	v_mul_f32_e32 v231, 0xbfb8aa3b, v42
	v_mul_f32_e32 v230, 0xbfb8aa3b, v51
	v_mul_f32_e32 v229, 0xbfb8aa3b, v43
	v_mul_f32_e32 v228, 0xbfb8aa3b, v18
	s_cbranch_scc0 .LBB0_145
	v_add_f32_e32 v178, 1.0, v171
	v_rcp_f32_e32 v179, v178
	v_add_f32_e32 v178, 1.0, v170
	v_add_f32_e32 v134, 1.0, v173
	v_add_f32_e32 v135, 1.0, v133
	v_add_f32_e32 v137, 1.0, v172
	v_rcp_f32_e32 v181, v178
	v_add_f32_e32 v178, 1.0, v169
	v_rcp_f32_e32 v134, v134
	v_rcp_f32_e32 v135, v135
	v_rcp_f32_e32 v137, v137
	v_rcp_f32_e32 v180, v178
	v_add_f32_e32 v178, 1.0, v131
	v_rcp_f32_e32 v182, v178
	v_mov_b32_e32 v0, v240
	v_mov_b32_e32 v136, v130
	v_cvt_pk_bf16_f32 v178, v132, v135
	v_cvt_pk_bf16_f32 v179, v179, v180
	v_cvt_pk_bf16_f32 v180, v134, v137
	v_mov_b64_e32 v[134:135], s[8:9]
	v_ashrrev_i32_e32 v137, 31, v136
	v_cvt_pk_bf16_f32 v181, v181, v182
	v_mad_i64_i32 v[182:183], s[0:1], v0, s47, v[134:135]
	v_lshlrev_b64 v[136:137], 1, v[136:137]
	v_lshl_add_u64 v[182:183], v[182:183], 0, v[136:137]
	global_store_dwordx4 v[182:183], v[178:181], off
	s_nop 1
	v_add_f32_e32 v179, 1.0, v167
	v_add_f32_e32 v178, 1.0, v168
	v_rcp_f32_e32 v180, v179
	v_add_f32_e32 v179, 1.0, v166
	v_add_f32_e32 v181, 1.0, v145
	v_add_f32_e32 v239, 1.0, v144
	v_add_f32_e32 v224, 1.0, v143
	v_add_f32_e32 v225, 1.0, v142
	v_add_f32_e32 v226, 1.0, v141
	v_rcp_f32_e32 v178, v178
	v_rcp_f32_e32 v179, v179
	v_rcp_f32_e32 v181, v181
	v_rcp_f32_e32 v239, v239
	v_rcp_f32_e32 v224, v224
	v_rcp_f32_e32 v225, v225
	v_rcp_f32_e32 v226, v226
	v_cvt_pk_bf16_f32 v178, v178, v179
	v_cvt_pk_bf16_f32 v180, v180, v181
	v_cvt_pk_bf16_f32 v179, v239, v225
	v_cvt_pk_bf16_f32 v181, v224, v226
	global_store_dwordx4 v[182:183], v[178:181], off offset:256
	s_nop 1
	v_add_f32_e32 v179, 1.0, v139
	v_add_f32_e32 v178, 1.0, v140
	v_rcp_f32_e32 v180, v179
	v_add_f32_e32 v179, 1.0, v138
	v_add_f32_e32 v183, 1.0, v155
	v_add_f32_e32 v225, 1.0, v153
	v_rcp_f32_e32 v178, v178
	v_rcp_f32_e32 v179, v179
	v_add_f32_e32 v181, 1.0, v213
	v_rcp_f32_e32 v183, v183
	v_add_f32_e32 v224, 1.0, v154
	v_rcp_f32_e32 v225, v225
	v_add_f32_e32 v226, 1.0, v152
	v_rcp_f32_e32 v181, v181
	v_rcp_f32_e32 v224, v224
	v_rcp_f32_e32 v226, v226
	v_add_u32_e32 v182, 16, v0
	v_cvt_pk_bf16_f32 v178, v178, v179
	v_cvt_pk_bf16_f32 v179, v183, v225
	v_mad_i64_i32 v[182:183], s[0:1], v182, s47, v[134:135]
	v_cvt_pk_bf16_f32 v180, v180, v181
	v_cvt_pk_bf16_f32 v181, v224, v226
	v_lshl_add_u64 v[182:183], v[182:183], 0, v[136:137]
	global_store_dwordx4 v[182:183], v[178:181], off
	s_nop 1
	v_add_f32_e32 v179, 1.0, v211
	v_add_f32_e32 v178, 1.0, v212
	v_rcp_f32_e32 v180, v179
	v_add_f32_e32 v179, 1.0, v252
	v_add_f32_e32 v181, 1.0, v251
	v_add_f32_e32 v224, 1.0, v250
	v_add_f32_e32 v225, 1.0, v249
	v_add_f32_e32 v226, 1.0, v248
	v_add_f32_e32 v239, 1.0, v247
	v_rcp_f32_e32 v178, v178
	v_rcp_f32_e32 v179, v179
	v_rcp_f32_e32 v181, v181
	v_rcp_f32_e32 v224, v224
	v_rcp_f32_e32 v225, v225
	v_rcp_f32_e32 v226, v226
	v_rcp_f32_e32 v239, v239
	v_cvt_pk_bf16_f32 v178, v178, v179
	v_cvt_pk_bf16_f32 v180, v180, v181
	v_cvt_pk_bf16_f32 v179, v224, v226
	v_cvt_pk_bf16_f32 v181, v225, v239
	global_store_dwordx4 v[182:183], v[178:181], off offset:256
	s_nop 1
	v_add_f32_e32 v179, 1.0, v245
	v_add_f32_e32 v178, 1.0, v246
	v_rcp_f32_e32 v180, v179
	v_add_f32_e32 v179, 1.0, v244
	v_add_f32_e32 v183, 1.0, v242
	v_add_f32_e32 v225, 1.0, v184
	v_rcp_f32_e32 v178, v178
	v_rcp_f32_e32 v179, v179
	v_add_f32_e32 v181, 1.0, v243
	v_rcp_f32_e32 v183, v183
	v_add_f32_e32 v224, 1.0, v241
	v_rcp_f32_e32 v225, v225
	v_add_f32_e32 v226, 1.0, v177
	v_rcp_f32_e32 v181, v181
	v_rcp_f32_e32 v224, v224
	v_rcp_f32_e32 v226, v226
	v_add_u32_e32 v182, 32, v0
	v_cvt_pk_bf16_f32 v178, v178, v179
	v_cvt_pk_bf16_f32 v179, v183, v225
	v_mad_i64_i32 v[182:183], s[0:1], v182, s47, v[134:135]
	v_cvt_pk_bf16_f32 v180, v180, v181
	v_cvt_pk_bf16_f32 v181, v224, v226
	v_lshl_add_u64 v[182:183], v[182:183], 0, v[136:137]
	global_store_dwordx4 v[182:183], v[178:181], off
	s_nop 1
	v_add_f32_e32 v179, 1.0, v199
	v_add_f32_e32 v178, 1.0, v198
	v_rcp_f32_e32 v180, v179
	v_add_f32_e32 v179, 1.0, v197
	v_add_f32_e32 v181, 1.0, v196
	v_add_f32_e32 v224, 1.0, v195
	v_add_f32_e32 v225, 1.0, v194
	v_add_f32_e32 v226, 1.0, v193
	v_add_f32_e32 v239, 1.0, v192
	v_rcp_f32_e32 v178, v178
	v_rcp_f32_e32 v179, v179
	v_rcp_f32_e32 v181, v181
	v_rcp_f32_e32 v224, v224
	v_rcp_f32_e32 v225, v225
	v_rcp_f32_e32 v226, v226
	v_rcp_f32_e32 v239, v239
	v_cvt_pk_bf16_f32 v178, v178, v179
	v_cvt_pk_bf16_f32 v180, v180, v181
	v_cvt_pk_bf16_f32 v179, v224, v226
	v_cvt_pk_bf16_f32 v181, v225, v239
	global_store_dwordx4 v[182:183], v[178:181], off offset:256
	s_nop 1
	v_add_f32_e32 v179, 1.0, v190
	v_add_f32_e32 v178, 1.0, v191
	v_rcp_f32_e32 v180, v179
	v_add_f32_e32 v179, 1.0, v189
	v_add_f32_e32 v183, 1.0, v187
	v_add_f32_e32 v225, 1.0, v185
	v_rcp_f32_e32 v178, v178
	v_rcp_f32_e32 v179, v179
	v_add_f32_e32 v181, 1.0, v188
	v_rcp_f32_e32 v183, v183
	v_add_f32_e32 v224, 1.0, v186
	v_rcp_f32_e32 v225, v225
	v_add_f32_e32 v226, 1.0, v201
	v_rcp_f32_e32 v181, v181
	v_rcp_f32_e32 v224, v224
	v_rcp_f32_e32 v226, v226
	v_add_u32_e32 v182, 48, v0
	v_cvt_pk_bf16_f32 v178, v178, v179
	v_cvt_pk_bf16_f32 v179, v183, v225
	v_mad_i64_i32 v[182:183], s[0:1], v182, s47, v[134:135]
	v_cvt_pk_bf16_f32 v180, v180, v181
	v_cvt_pk_bf16_f32 v181, v224, v226
	v_lshl_add_u64 v[182:183], v[182:183], 0, v[136:137]
	global_store_dwordx4 v[182:183], v[178:181], off
	s_nop 1
	v_add_f32_e32 v179, 1.0, v221
	v_add_f32_e32 v178, 1.0, v200
	v_rcp_f32_e32 v180, v179
	v_add_f32_e32 v179, 1.0, v220
	v_add_f32_e32 v181, 1.0, v219
	v_add_f32_e32 v224, 1.0, v218
	v_add_f32_e32 v225, 1.0, v217
	v_add_f32_e32 v226, 1.0, v216
	v_add_f32_e32 v239, 1.0, v215
	v_rcp_f32_e32 v178, v178
	v_rcp_f32_e32 v179, v179
	v_rcp_f32_e32 v181, v181
	v_rcp_f32_e32 v224, v224
	v_rcp_f32_e32 v225, v225
	v_rcp_f32_e32 v226, v226
	v_rcp_f32_e32 v239, v239
	v_cvt_pk_bf16_f32 v178, v178, v179
	v_cvt_pk_bf16_f32 v180, v180, v181
	v_cvt_pk_bf16_f32 v179, v224, v226
	v_cvt_pk_bf16_f32 v181, v225, v239
	global_store_dwordx4 v[182:183], v[178:181], off offset:256
	s_nop 1
	v_add_f32_e32 v179, 1.0, v208
	v_add_f32_e32 v178, 1.0, v209
	v_rcp_f32_e32 v180, v179
	v_add_f32_e32 v179, 1.0, v207
	v_add_f32_e32 v183, 1.0, v205
	v_add_f32_e32 v225, 1.0, v203
	v_rcp_f32_e32 v178, v178
	v_rcp_f32_e32 v179, v179
	v_add_f32_e32 v181, 1.0, v206
	v_rcp_f32_e32 v183, v183
	v_add_f32_e32 v224, 1.0, v204
	v_rcp_f32_e32 v225, v225
	v_add_f32_e32 v226, 1.0, v202
	v_rcp_f32_e32 v181, v181
	v_rcp_f32_e32 v224, v224
	v_rcp_f32_e32 v226, v226
	v_add_u32_e32 v182, 0x80, v0
	v_cvt_pk_bf16_f32 v178, v178, v179
	v_cvt_pk_bf16_f32 v179, v183, v225
	v_mad_i64_i32 v[182:183], s[0:1], v182, s47, v[134:135]
	v_cvt_pk_bf16_f32 v180, v180, v181
	v_cvt_pk_bf16_f32 v181, v224, v226
	v_lshl_add_u64 v[182:183], v[182:183], 0, v[136:137]
	global_store_dwordx4 v[182:183], v[178:181], off
	s_nop 1
	v_add_f32_e32 v179, 1.0, v222
	v_rcp_f32_e32 v180, v179
	v_exp_f32_e32 v179, v237
	v_exp_f32_e32 v224, v236
	v_exp_f32_e32 v226, v234
	v_exp_f32_e32 v239, v233
	v_add_f32_e32 v179, 1.0, v179
	v_rcp_f32_e32 v225, v179
	v_exp_f32_e32 v179, v235
	v_add_f32_e32 v178, 1.0, v223
	v_add_f32_e32 v181, 1.0, v238
	v_add_f32_e32 v224, 1.0, v224
	v_add_f32_e32 v179, 1.0, v179
	v_rcp_f32_e32 v227, v179
	v_add_f32_e32 v179, 1.0, v226
	v_add_f32_e32 v226, 1.0, v239
	v_rcp_f32_e32 v178, v178
	v_rcp_f32_e32 v181, v181
	v_rcp_f32_e32 v224, v224
	v_rcp_f32_e32 v179, v179
	v_rcp_f32_e32 v226, v226
	v_cvt_pk_bf16_f32 v178, v178, v181
	v_cvt_pk_bf16_f32 v180, v180, v225
	v_cvt_pk_bf16_f32 v179, v224, v179
	v_cvt_pk_bf16_f32 v181, v227, v226
	global_store_dwordx4 v[182:183], v[178:181], off offset:256
	s_nop 1
	v_exp_f32_e32 v179, v231
	v_mul_f32_e32 v183, 0xbfb8aa3b, v52
	v_mul_f32_e32 v225, 0xbfb8aa3b, v53
	v_exp_f32_e32 v183, v183
	v_add_f32_e32 v179, 1.0, v179
	v_rcp_f32_e32 v181, v179
	v_exp_f32_e32 v179, v229
	v_exp_f32_e32 v225, v225
	v_mul_f32_e32 v226, 0xbfb8aa3b, v45
	v_exp_f32_e32 v178, v232
	v_add_f32_e32 v179, 1.0, v179
	v_rcp_f32_e32 v224, v179
	v_mul_f32_e32 v179, 0xbfb8aa3b, v44
	v_exp_f32_e32 v179, v179
	v_exp_f32_e32 v180, v230
	v_exp_f32_e32 v226, v226
	v_add_f32_e32 v183, 1.0, v183
	v_add_f32_e32 v179, 1.0, v179
	v_rcp_f32_e32 v227, v179
	v_add_f32_e32 v179, 1.0, v225
	v_add_f32_e32 v178, 1.0, v178
	v_add_f32_e32 v180, 1.0, v180
	v_rcp_f32_e32 v183, v183
	v_rcp_f32_e32 v179, v179
	v_add_f32_e32 v225, 1.0, v226
	v_rcp_f32_e32 v178, v178
	v_rcp_f32_e32 v180, v180
	v_rcp_f32_e32 v225, v225
	v_add_u32_e32 v182, 0x90, v0
	v_cvt_pk_bf16_f32 v179, v183, v179
	v_mad_i64_i32 v[182:183], s[0:1], v182, s47, v[134:135]
	v_cvt_pk_bf16_f32 v178, v178, v180
	v_cvt_pk_bf16_f32 v180, v181, v224
	v_cvt_pk_bf16_f32 v181, v227, v225
	v_lshl_add_u64 v[182:183], v[182:183], 0, v[136:137]
	global_store_dwordx4 v[182:183], v[178:181], off
	s_nop 1
	v_mul_f32_e32 v179, 0xbfb8aa3b, v30
	v_exp_f32_e32 v179, v179
	v_mul_f32_e32 v178, 0xbfb8aa3b, v38
	v_mul_f32_e32 v180, 0xbfb8aa3b, v39
	v_mul_f32_e32 v224, 0xbfb8aa3b, v40
	v_add_f32_e32 v179, 1.0, v179
	v_rcp_f32_e32 v181, v179
	v_mul_f32_e32 v179, 0xbfb8aa3b, v31
	v_exp_f32_e32 v179, v179
	v_mul_f32_e32 v226, 0xbfb8aa3b, v41
	v_mul_f32_e32 v227, 0xbfb8aa3b, v33
	v_exp_f32_e32 v178, v178
	v_add_f32_e32 v179, 1.0, v179
	v_rcp_f32_e32 v225, v179
	v_mul_f32_e32 v179, 0xbfb8aa3b, v32
	v_exp_f32_e32 v179, v179
	v_exp_f32_e32 v180, v180
	v_exp_f32_e32 v224, v224
	v_exp_f32_e32 v226, v226
	v_exp_f32_e32 v227, v227
	v_add_f32_e32 v179, 1.0, v179
	v_add_f32_e32 v178, 1.0, v178
	v_add_f32_e32 v180, 1.0, v180
	v_add_f32_e32 v224, 1.0, v224
	v_rcp_f32_e32 v239, v179
	v_add_f32_e32 v179, 1.0, v226
	v_add_f32_e32 v226, 1.0, v227
	v_rcp_f32_e32 v178, v178
	v_rcp_f32_e32 v180, v180
	v_rcp_f32_e32 v224, v224
	v_rcp_f32_e32 v179, v179
	v_rcp_f32_e32 v226, v226
	v_cvt_pk_bf16_f32 v178, v178, v180
	v_cvt_pk_bf16_f32 v180, v181, v225
	v_cvt_pk_bf16_f32 v179, v224, v179
	v_cvt_pk_bf16_f32 v181, v239, v226
	global_store_dwordx4 v[182:183], v[178:181], off offset:256
	s_nop 1
	v_mul_f32_e32 v179, 0xbfb8aa3b, v26
	v_exp_f32_e32 v179, v179
	v_mul_f32_e32 v183, 0xbfb8aa3b, v36
	v_mul_f32_e32 v225, 0xbfb8aa3b, v37
	v_mul_f32_e32 v178, 0xbfb8aa3b, v34
	v_add_f32_e32 v179, 1.0, v179
	v_rcp_f32_e32 v181, v179
	v_mul_f32_e32 v179, 0xbfb8aa3b, v27
	v_exp_f32_e32 v179, v179
	v_mul_f32_e32 v180, 0xbfb8aa3b, v35
	v_exp_f32_e32 v183, v183
	v_exp_f32_e32 v225, v225
	v_add_f32_e32 v179, 1.0, v179
	v_rcp_f32_e32 v224, v179
	v_mul_f32_e32 v179, 0xbfb8aa3b, v28
	v_exp_f32_e32 v179, v179
	v_mul_f32_e32 v226, 0xbfb8aa3b, v29
	v_exp_f32_e32 v178, v178
	v_exp_f32_e32 v180, v180
	v_exp_f32_e32 v226, v226
	v_add_f32_e32 v179, 1.0, v179
	v_add_f32_e32 v183, 1.0, v183
	v_rcp_f32_e32 v227, v179
	v_add_f32_e32 v179, 1.0, v225
	v_add_f32_e32 v178, 1.0, v178
	v_add_f32_e32 v180, 1.0, v180
	v_rcp_f32_e32 v183, v183
	v_rcp_f32_e32 v179, v179
	v_add_f32_e32 v225, 1.0, v226
	v_rcp_f32_e32 v178, v178
	v_rcp_f32_e32 v180, v180
	v_rcp_f32_e32 v225, v225
	v_add_u32_e32 v182, 0xa0, v0
	v_cvt_pk_bf16_f32 v179, v183, v179
	v_mad_i64_i32 v[182:183], s[0:1], v182, s47, v[134:135]
	v_cvt_pk_bf16_f32 v178, v178, v180
	v_cvt_pk_bf16_f32 v180, v181, v224
	v_cvt_pk_bf16_f32 v181, v227, v225
	v_lshl_add_u64 v[182:183], v[182:183], 0, v[136:137]
	global_store_dwordx4 v[182:183], v[178:181], off
	s_nop 1
	v_mul_f32_e32 v179, 0xbfb8aa3b, v14
	v_exp_f32_e32 v179, v179
	v_mul_f32_e32 v178, 0xbfb8aa3b, v22
	v_mul_f32_e32 v180, 0xbfb8aa3b, v23
	v_mul_f32_e32 v224, 0xbfb8aa3b, v24
	v_add_f32_e32 v179, 1.0, v179
	v_rcp_f32_e32 v181, v179
	v_mul_f32_e32 v179, 0xbfb8aa3b, v15
	v_exp_f32_e32 v179, v179
	v_mul_f32_e32 v226, 0xbfb8aa3b, v25
	v_mul_f32_e32 v227, 0xbfb8aa3b, v17
	v_exp_f32_e32 v178, v178
	v_add_f32_e32 v179, 1.0, v179
	v_rcp_f32_e32 v225, v179
	v_mul_f32_e32 v179, 0xbfb8aa3b, v16
	v_exp_f32_e32 v179, v179
	v_exp_f32_e32 v180, v180
	v_exp_f32_e32 v224, v224
	v_exp_f32_e32 v226, v226
	v_exp_f32_e32 v227, v227
	v_add_f32_e32 v179, 1.0, v179
	v_add_f32_e32 v178, 1.0, v178
	v_add_f32_e32 v180, 1.0, v180
	v_add_f32_e32 v224, 1.0, v224
	v_rcp_f32_e32 v239, v179
	v_add_f32_e32 v179, 1.0, v226
	v_add_f32_e32 v226, 1.0, v227
	v_rcp_f32_e32 v178, v178
	v_rcp_f32_e32 v180, v180
	v_rcp_f32_e32 v224, v224
	v_rcp_f32_e32 v179, v179
	v_rcp_f32_e32 v226, v226
	v_cvt_pk_bf16_f32 v178, v178, v180
	v_cvt_pk_bf16_f32 v180, v181, v225
	v_cvt_pk_bf16_f32 v179, v224, v179
	v_cvt_pk_bf16_f32 v181, v239, v226
	global_store_dwordx4 v[182:183], v[178:181], off offset:256
	s_nop 1
	v_mul_f32_e32 v179, 0xbfb8aa3b, v10
	v_exp_f32_e32 v179, v179
	v_mul_f32_e32 v180, 0xbfb8aa3b, v19
	v_mul_f32_e32 v181, 0xbfb8aa3b, v11
	v_exp_f32_e32 v180, v180
	v_exp_f32_e32 v181, v181
	v_add_f32_e32 v179, 1.0, v179
	v_rcp_f32_e32 v182, v179
	v_add_f32_e32 v179, 1.0, v180
	v_add_f32_e32 v180, 1.0, v181
	v_mul_f32_e32 v181, 0xbfb8aa3b, v20
	v_mul_f32_e32 v183, 0xbfb8aa3b, v12
	v_mul_f32_e32 v224, 0xbfb8aa3b, v21
	v_mul_f32_e32 v225, 0xbfb8aa3b, v13
	v_exp_f32_e32 v178, v228
	v_exp_f32_e32 v181, v181
	v_exp_f32_e32 v183, v183
	v_exp_f32_e32 v224, v224
	v_exp_f32_e32 v225, v225
	v_add_f32_e32 v178, 1.0, v178
	v_add_f32_e32 v181, 1.0, v181
	v_add_f32_e32 v183, 1.0, v183
	v_add_f32_e32 v224, 1.0, v224
	v_add_f32_e32 v225, 1.0, v225
	v_rcp_f32_e32 v178, v178
	v_rcp_f32_e32 v179, v179
	v_rcp_f32_e32 v180, v180
	v_rcp_f32_e32 v181, v181
	v_rcp_f32_e32 v183, v183
	v_rcp_f32_e32 v224, v224
	v_rcp_f32_e32 v225, v225
	v_add_u32_e32 v0, 0xb0, v0
	v_mad_i64_i32 v[134:135], s[0:1], v0, s47, v[134:135]
	v_cvt_pk_bf16_f32 v178, v178, v179
	v_cvt_pk_bf16_f32 v179, v181, v224
	v_cvt_pk_bf16_f32 v180, v182, v180
	v_cvt_pk_bf16_f32 v181, v183, v225
	v_lshl_add_u64 v[182:183], v[134:135], 0, v[136:137]
	global_store_dwordx4 v[182:183], v[178:181], off
	v_mul_f32_e32 v134, 0xbfb8aa3b, v2
	v_exp_f32_e32 v134, v134
	v_mul_f32_e32 v135, 0xbfb8aa3b, v7
	v_mul_f32_e32 v136, 0xbfb8aa3b, v3
	v_exp_f32_e32 v135, v135
	v_exp_f32_e32 v136, v136
	v_add_f32_e32 v134, 1.0, v134
	v_rcp_f32_e32 v137, v134
	v_add_f32_e32 v134, 1.0, v135
	v_add_f32_e32 v135, 1.0, v136
	v_mul_f32_e32 v136, 0xbfb8aa3b, v8
	v_mul_f32_e32 v178, 0xbfb8aa3b, v4
	v_exp_f32_e32 v136, v136
	v_exp_f32_e32 v178, v178
	v_mul_f32_e32 v0, 0xbfb8aa3b, v6
	v_rcp_f32_e32 v179, v135
	v_add_f32_e32 v135, 1.0, v136
	v_add_f32_e32 v136, 1.0, v178
	v_mul_f32_e32 v178, 0xbfb8aa3b, v9
	v_mul_f32_e32 v180, 0xbfb8aa3b, v5
	v_exp_f32_e32 v0, v0
	v_exp_f32_e32 v178, v178
	v_exp_f32_e32 v180, v180
	v_rcp_f32_e32 v181, v136
	v_add_f32_e32 v0, 1.0, v0
	v_add_f32_e32 v136, 1.0, v178
	v_add_f32_e32 v178, 1.0, v180
	v_rcp_f32_e32 v0, v0
	v_rcp_f32_e32 v134, v134
	v_rcp_f32_e32 v135, v135
	v_rcp_f32_e32 v136, v136
	v_rcp_f32_e32 v178, v178
	v_cvt_pk_bf16_f32 v134, v0, v134
	v_cvt_pk_bf16_f32 v135, v135, v136
	v_cvt_pk_bf16_f32 v136, v137, v179
	v_cvt_pk_bf16_f32 v137, v181, v178
	global_store_dwordx4 v[182:183], v[134:137], off offset:256
	s_mov_b64 s[0:1], 0

.LBB0_938:
	s_ashr_i32 s23, s22, 31
	s_lshl_b64 s[28:29], s[22:23], 20
	s_add_u32 s28, s8, s28
	s_addc_u32 s29, s9, s29
	s_and_b64 s[38:39], s[42:43], exec
	s_cselect_b32 s23, s29, s37
	s_cselect_b32 s42, s28, s36
	s_add_u32 s30, s30, 0x80080
	s_addc_u32 s31, s31, 0
	s_add_u32 s43, s36, 0x100
	v_mov_b32_e32 v2, 0
	s_addc_u32 s67, s37, 0
	s_mov_b32 s68, -2
	v_mov_b32_e32 v3, v2
	v_mov_b32_e32 v4, v2
	v_mov_b32_e32 v5, v2
	v_mov_b32_e32 v6, v2
	v_mov_b32_e32 v7, v2
	v_mov_b32_e32 v8, v2
	v_mov_b32_e32 v9, v2
	v_mov_b32_e32 v10, v2
	v_mov_b32_e32 v11, v2
	v_mov_b32_e32 v12, v2
	v_mov_b32_e32 v13, v2
	v_mov_b32_e32 v14, v2
	v_mov_b32_e32 v15, v2
	v_mov_b32_e32 v16, v2
	v_mov_b32_e32 v17, v2
	v_mov_b32_e32 v26, v2
	v_mov_b32_e32 v27, v2
	v_mov_b32_e32 v28, v2
	v_mov_b32_e32 v29, v2
	v_mov_b32_e32 v30, v2
	v_mov_b32_e32 v31, v2
	v_mov_b32_e32 v32, v2
	v_mov_b32_e32 v33, v2
	v_mov_b32_e32 v42, v2
	v_mov_b32_e32 v43, v2
	v_mov_b32_e32 v44, v2
	v_mov_b32_e32 v45, v2
	v_mov_b32_e32 v46, v2
	v_mov_b32_e32 v47, v2
	v_mov_b32_e32 v48, v2
	v_mov_b32_e32 v49, v2
	v_mov_b32_e32 v18, v2
	v_mov_b32_e32 v19, v2
	v_mov_b32_e32 v20, v2
	v_mov_b32_e32 v21, v2
	v_mov_b32_e32 v22, v2
	v_mov_b32_e32 v23, v2
	v_mov_b32_e32 v24, v2
	v_mov_b32_e32 v25, v2
	v_mov_b32_e32 v34, v2
	v_mov_b32_e32 v35, v2
	v_mov_b32_e32 v36, v2
	v_mov_b32_e32 v37, v2
	v_mov_b32_e32 v38, v2
	v_mov_b32_e32 v39, v2
	v_mov_b32_e32 v40, v2
	v_mov_b32_e32 v41, v2
	v_mov_b32_e32 v50, v2
	v_mov_b32_e32 v51, v2
	v_mov_b32_e32 v52, v2
	v_mov_b32_e32 v53, v2
	v_mov_b32_e32 v54, v2
	v_mov_b32_e32 v55, v2
	v_mov_b32_e32 v56, v2
	v_mov_b32_e32 v57, v2
	v_mov_b32_e32 v58, v2
	v_mov_b32_e32 v59, v2
	v_mov_b32_e32 v60, v2
	v_mov_b32_e32 v61, v2
	v_mov_b32_e32 v62, v2
	v_mov_b32_e32 v63, v2
	v_mov_b32_e32 v64, v2
	v_mov_b32_e32 v65, v2
	v_mov_b32_e32 v66, v2
	v_mov_b32_e32 v67, v2
	v_mov_b32_e32 v68, v2
	v_mov_b32_e32 v69, v2
	v_mov_b32_e32 v70, v2
	v_mov_b32_e32 v71, v2
	v_mov_b32_e32 v72, v2
	v_mov_b32_e32 v73, v2
	v_mov_b32_e32 v74, v2
	v_mov_b32_e32 v75, v2
	v_mov_b32_e32 v76, v2
	v_mov_b32_e32 v77, v2
	v_mov_b32_e32 v78, v2
	v_mov_b32_e32 v79, v2
	v_mov_b32_e32 v80, v2
	v_mov_b32_e32 v81, v2
	v_mov_b32_e32 v90, v2
	v_mov_b32_e32 v91, v2
	v_mov_b32_e32 v92, v2
	v_mov_b32_e32 v93, v2
	v_mov_b32_e32 v94, v2
	v_mov_b32_e32 v95, v2
	v_mov_b32_e32 v96, v2
	v_mov_b32_e32 v97, v2
	v_mov_b32_e32 v106, v2
	v_mov_b32_e32 v107, v2
	v_mov_b32_e32 v108, v2
	v_mov_b32_e32 v109, v2
	v_mov_b32_e32 v110, v2
	v_mov_b32_e32 v111, v2
	v_mov_b32_e32 v112, v2
	v_mov_b32_e32 v113, v2
	v_mov_b32_e32 v82, v2
	v_mov_b32_e32 v83, v2
	v_mov_b32_e32 v84, v2
	v_mov_b32_e32 v85, v2
	v_mov_b32_e32 v86, v2
	v_mov_b32_e32 v87, v2
	v_mov_b32_e32 v88, v2
	v_mov_b32_e32 v89, v2
	v_mov_b32_e32 v98, v2
	v_mov_b32_e32 v99, v2
	v_mov_b32_e32 v100, v2
	v_mov_b32_e32 v101, v2
	v_mov_b32_e32 v102, v2
	v_mov_b32_e32 v103, v2
	v_mov_b32_e32 v104, v2
	v_mov_b32_e32 v105, v2
	v_mov_b32_e32 v114, v2
	v_mov_b32_e32 v115, v2
	v_mov_b32_e32 v116, v2
	v_mov_b32_e32 v117, v2
	v_mov_b32_e32 v118, v2
	v_mov_b32_e32 v119, v2
	v_mov_b32_e32 v120, v2
	v_mov_b32_e32 v121, v2
	v_mov_b32_e32 v122, v2
	v_mov_b32_e32 v123, v2
	v_mov_b32_e32 v124, v2
	v_mov_b32_e32 v125, v2
	v_mov_b32_e32 v126, v2
	v_mov_b32_e32 v127, v2
	v_mov_b32_e32 v128, v2
	v_mov_b32_e32 v129, v2
	v_add_u32_e32 v224, 0x10000, v140
	v_add_u32_e32 v225, 0x14000, v140
	v_add_u32_e32 v226, 0x18000, v140
	v_add_u32_e32 v227, 0x1c000, v140
	s_add_i32 s78, s40, 0x10000
	s_add_i32 s80, s40, 0x14000
	s_add_i32 s82, s40, 0x18000
	s_add_i32 s83, s40, 0x1c000
.LBB0_939:
	s_add_u32 s36, s30, 0xfff80080
	s_addc_u32 s37, s31, -1
	ds_read_b128 v[142:145], v224
	ds_read_b128 v[152:155], v224 offset:1024
	ds_read_b128 v[156:159], v224 offset:2048
	ds_read_b128 v[160:163], v224 offset:3072
	s_cmp_eq_u32 s68, 28
	s_cselect_b32 s39, s27, s37
	s_cselect_b32 s38, s26, s36
	s_cselect_b32 s37, s23, s67
	s_cselect_b32 s36, s42, s43
	s_add_i32 m0, s41, 0xc000
	ds_read_b128 v[164:167], v141
	ds_read_b128 v[168:171], v141 offset:1024
	ds_read_b128 v[172:175], v141 offset:2048
	ds_read_b128 v[176:179], v141 offset:3072
	ds_read_b128 v[180:183], v141 offset:4096
	ds_read_b128 v[184:187], v141 offset:5120
	ds_read_b128 v[188:191], v141 offset:6144
	global_load_lds_dwordx4 v136, s[30:31]
	s_add_i32 m0, s41, 0xe000
	ds_read_b128 v[192:195], v141 offset:7168
	global_load_lds_dwordx4 v138, s[30:31]
	s_waitcnt lgkmcnt(8)
	s_barrier
	s_waitcnt lgkmcnt(7)
	v_mfma_f32_16x16x32_bf16 v[126:129], v[142:145], v[164:167], v[126:129]
	v_mfma_f32_16x16x32_bf16 v[122:125], v[156:159], v[164:167], v[122:125]
	s_waitcnt lgkmcnt(5)
	v_mfma_f32_16x16x32_bf16 v[118:121], v[142:145], v[172:175], v[118:121]
	v_mfma_f32_16x16x32_bf16 v[114:117], v[156:159], v[172:175], v[114:117]
	s_waitcnt lgkmcnt(3)
	v_mfma_f32_16x16x32_bf16 v[102:105], v[142:145], v[180:183], v[102:105]
	v_mfma_f32_16x16x32_bf16 v[98:101], v[156:159], v[180:183], v[98:101]
	s_waitcnt lgkmcnt(1)
	v_mfma_f32_16x16x32_bf16 v[86:89], v[142:145], v[188:191], v[86:89]
	v_mfma_f32_16x16x32_bf16 v[82:85], v[156:159], v[188:191], v[82:85]
	v_mfma_f32_16x16x32_bf16 v[126:129], v[152:155], v[168:171], v[126:129]
	v_mfma_f32_16x16x32_bf16 v[122:125], v[160:163], v[168:171], v[122:125]
	v_mfma_f32_16x16x32_bf16 v[118:121], v[152:155], v[176:179], v[118:121]
	v_mfma_f32_16x16x32_bf16 v[114:117], v[160:163], v[176:179], v[114:117]
	v_mfma_f32_16x16x32_bf16 v[102:105], v[152:155], v[184:187], v[102:105]
	v_mfma_f32_16x16x32_bf16 v[98:101], v[160:163], v[184:187], v[98:101]
	s_waitcnt lgkmcnt(0)
	v_mfma_f32_16x16x32_bf16 v[86:89], v[152:155], v[192:195], v[86:89]
	v_mfma_f32_16x16x32_bf16 v[82:85], v[160:163], v[192:195], v[82:85]
	s_barrier
	ds_read_b128 v[196:199], v225
	ds_read_b128 v[200:203], v225 offset:1024
	ds_read_b128 v[204:207], v225 offset:2048
	ds_read_b128 v[216:219], v225 offset:3072
	s_mov_b32 m0, s78
	s_nop 0
	global_load_lds_dwordx4 v0, s[36:37]
	s_add_i32 m0, s78, 0x2000
	s_nop 0
	global_load_lds_dwordx4 v130, s[36:37]
	s_barrier
	s_waitcnt lgkmcnt(3)
	v_mfma_f32_16x16x32_bf16 v[110:113], v[196:199], v[164:167], v[110:113]
	s_waitcnt lgkmcnt(1)
	v_mfma_f32_16x16x32_bf16 v[106:109], v[204:207], v[164:167], v[106:109]
	v_mfma_f32_16x16x32_bf16 v[94:97], v[196:199], v[172:175], v[94:97]
	v_mfma_f32_16x16x32_bf16 v[90:93], v[204:207], v[172:175], v[90:93]
	v_mfma_f32_16x16x32_bf16 v[78:81], v[196:199], v[180:183], v[78:81]
	v_mfma_f32_16x16x32_bf16 v[74:77], v[204:207], v[180:183], v[74:77]
	v_mfma_f32_16x16x32_bf16 v[70:73], v[196:199], v[188:191], v[70:73]
	v_mfma_f32_16x16x32_bf16 v[66:69], v[204:207], v[188:191], v[66:69]
	v_mfma_f32_16x16x32_bf16 v[110:113], v[200:203], v[168:171], v[110:113]
	s_waitcnt lgkmcnt(0)
	v_mfma_f32_16x16x32_bf16 v[106:109], v[216:219], v[168:171], v[106:109]
	v_mfma_f32_16x16x32_bf16 v[94:97], v[200:203], v[176:179], v[94:97]
	v_mfma_f32_16x16x32_bf16 v[90:93], v[216:219], v[176:179], v[90:93]
	v_mfma_f32_16x16x32_bf16 v[78:81], v[200:203], v[184:187], v[78:81]
	v_mfma_f32_16x16x32_bf16 v[74:77], v[216:219], v[184:187], v[74:77]
	v_mfma_f32_16x16x32_bf16 v[70:73], v[200:203], v[192:195], v[70:73]
	v_mfma_f32_16x16x32_bf16 v[66:69], v[216:219], v[192:195], v[66:69]
	s_mov_b32 m0, s41
	s_add_u32 s98, s38, 0x80
	s_addc_u32 s99, s39, 0
	s_barrier
	ds_read_b128 v[164:167], v141 offset:16384
	ds_read_b128 v[168:171], v141 offset:17408
	ds_read_b128 v[172:175], v141 offset:18432
	ds_read_b128 v[176:179], v141 offset:19456
	ds_read_b128 v[180:183], v141 offset:20480
	ds_read_b128 v[184:187], v141 offset:21504
	ds_read_b128 v[188:191], v141 offset:22528
	global_load_lds_dwordx4 v134, s[38:39]
	s_mov_b32 m0, s44
	ds_read_b128 v[192:195], v141 offset:23552
	global_load_lds_dwordx4 v132, s[38:39]
	s_barrier
	s_waitcnt lgkmcnt(7)
	v_mfma_f32_16x16x32_bf16 v[62:65], v[142:145], v[164:167], v[62:65]
	v_mfma_f32_16x16x32_bf16 v[58:61], v[156:159], v[164:167], v[58:61]
	s_waitcnt lgkmcnt(5)
	v_mfma_f32_16x16x32_bf16 v[54:57], v[142:145], v[172:175], v[54:57]
	v_mfma_f32_16x16x32_bf16 v[50:53], v[156:159], v[172:175], v[50:53]
	s_waitcnt lgkmcnt(3)
	v_mfma_f32_16x16x32_bf16 v[38:41], v[142:145], v[180:183], v[38:41]
	v_mfma_f32_16x16x32_bf16 v[34:37], v[156:159], v[180:183], v[34:37]
	s_waitcnt lgkmcnt(1)
	v_mfma_f32_16x16x32_bf16 v[22:25], v[142:145], v[188:191], v[22:25]
	v_mfma_f32_16x16x32_bf16 v[18:21], v[156:159], v[188:191], v[18:21]
	v_mfma_f32_16x16x32_bf16 v[62:65], v[152:155], v[168:171], v[62:65]
	v_mfma_f32_16x16x32_bf16 v[58:61], v[160:163], v[168:171], v[58:61]
	v_mfma_f32_16x16x32_bf16 v[54:57], v[152:155], v[176:179], v[54:57]
	v_mfma_f32_16x16x32_bf16 v[50:53], v[160:163], v[176:179], v[50:53]
	v_mfma_f32_16x16x32_bf16 v[38:41], v[152:155], v[184:187], v[38:41]
	v_mfma_f32_16x16x32_bf16 v[34:37], v[160:163], v[184:187], v[34:37]
	s_waitcnt lgkmcnt(0)
	v_mfma_f32_16x16x32_bf16 v[22:25], v[152:155], v[192:195], v[22:25]
	v_mfma_f32_16x16x32_bf16 v[18:21], v[160:163], v[192:195], v[18:21]
	s_barrier
	s_mov_b32 m0, s80
	s_add_u32 s76, s36, 0x80000
	s_addc_u32 s77, s37, 0
	global_load_lds_dwordx4 v0, s[76:77]
	s_add_i32 m0, s80, 0x2000
	s_nop 0
	global_load_lds_dwordx4 v130, s[76:77]
	s_waitcnt vmcnt(6)
	s_barrier
	v_mfma_f32_16x16x32_bf16 v[46:49], v[196:199], v[164:167], v[46:49]
	v_mfma_f32_16x16x32_bf16 v[42:45], v[204:207], v[164:167], v[42:45]
	v_mfma_f32_16x16x32_bf16 v[30:33], v[196:199], v[172:175], v[30:33]
	v_mfma_f32_16x16x32_bf16 v[26:29], v[204:207], v[172:175], v[26:29]
	v_mfma_f32_16x16x32_bf16 v[14:17], v[196:199], v[180:183], v[14:17]
	v_mfma_f32_16x16x32_bf16 v[10:13], v[204:207], v[180:183], v[10:13]
	v_mfma_f32_16x16x32_bf16 v[6:9], v[196:199], v[188:191], v[6:9]
	v_mfma_f32_16x16x32_bf16 v[2:5], v[204:207], v[188:191], v[2:5]
	v_mfma_f32_16x16x32_bf16 v[46:49], v[200:203], v[168:171], v[46:49]
	v_mfma_f32_16x16x32_bf16 v[42:45], v[216:219], v[168:171], v[42:45]
	v_mfma_f32_16x16x32_bf16 v[30:33], v[200:203], v[176:179], v[30:33]
	v_mfma_f32_16x16x32_bf16 v[26:29], v[216:219], v[176:179], v[26:29]
	v_mfma_f32_16x16x32_bf16 v[14:17], v[200:203], v[184:187], v[14:17]
	v_mfma_f32_16x16x32_bf16 v[10:13], v[216:219], v[184:187], v[10:13]
	v_mfma_f32_16x16x32_bf16 v[6:9], v[200:203], v[192:195], v[6:9]
	v_mfma_f32_16x16x32_bf16 v[2:5], v[216:219], v[192:195], v[2:5]
	s_barrier
	ds_read_b128 v[142:145], v226
	ds_read_b128 v[152:155], v226 offset:1024
	ds_read_b128 v[156:159], v226 offset:2048
	ds_read_b128 v[160:163], v226 offset:3072
	s_add_u32 s38, s38, 0x80000
	s_addc_u32 s39, s39, 0
	s_mov_b32 m0, s45
	ds_read_b128 v[164:167], v141 offset:32768
	ds_read_b128 v[168:171], v141 offset:33792
	ds_read_b128 v[172:175], v141 offset:34816
	ds_read_b128 v[176:179], v141 offset:35840
	ds_read_b128 v[180:183], v141 offset:36864
	ds_read_b128 v[184:187], v141 offset:37888
	ds_read_b128 v[188:191], v141 offset:38912
	global_load_lds_dwordx4 v134, s[38:39]
	s_mov_b32 m0, s50
	ds_read_b128 v[192:195], v141 offset:39936
	global_load_lds_dwordx4 v132, s[38:39]
	s_waitcnt lgkmcnt(8)
	s_barrier
	s_waitcnt lgkmcnt(7)
	v_mfma_f32_16x16x32_bf16 v[126:129], v[142:145], v[164:167], v[126:129]
	v_mfma_f32_16x16x32_bf16 v[122:125], v[156:159], v[164:167], v[122:125]
	s_waitcnt lgkmcnt(5)
	v_mfma_f32_16x16x32_bf16 v[118:121], v[142:145], v[172:175], v[118:121]
	v_mfma_f32_16x16x32_bf16 v[114:117], v[156:159], v[172:175], v[114:117]
	s_waitcnt lgkmcnt(3)
	v_mfma_f32_16x16x32_bf16 v[102:105], v[142:145], v[180:183], v[102:105]
	v_mfma_f32_16x16x32_bf16 v[98:101], v[156:159], v[180:183], v[98:101]
	s_waitcnt lgkmcnt(1)
	v_mfma_f32_16x16x32_bf16 v[86:89], v[142:145], v[188:191], v[86:89]
	v_mfma_f32_16x16x32_bf16 v[82:85], v[156:159], v[188:191], v[82:85]
	v_mfma_f32_16x16x32_bf16 v[126:129], v[152:155], v[168:171], v[126:129]
	v_mfma_f32_16x16x32_bf16 v[122:125], v[160:163], v[168:171], v[122:125]
	v_mfma_f32_16x16x32_bf16 v[118:121], v[152:155], v[176:179], v[118:121]
	v_mfma_f32_16x16x32_bf16 v[114:117], v[160:163], v[176:179], v[114:117]
	v_mfma_f32_16x16x32_bf16 v[102:105], v[152:155], v[184:187], v[102:105]
	v_mfma_f32_16x16x32_bf16 v[98:101], v[160:163], v[184:187], v[98:101]
	s_waitcnt lgkmcnt(0)
	v_mfma_f32_16x16x32_bf16 v[86:89], v[152:155], v[192:195], v[86:89]
	v_mfma_f32_16x16x32_bf16 v[82:85], v[160:163], v[192:195], v[82:85]
	s_barrier
	s_add_u32 s100, s36, 0x80
	s_addc_u32 s101, s37, 0
	s_mov_b32 m0, s82
	ds_read_b128 v[196:199], v227
	ds_read_b128 v[200:203], v227 offset:1024
	ds_read_b128 v[204:207], v227 offset:2048
	global_load_lds_dwordx4 v0, s[100:101]
	s_add_i32 m0, s82, 0x2000
	ds_read_b128 v[216:219], v227 offset:3072
	global_load_lds_dwordx4 v130, s[100:101]
	s_barrier
	s_waitcnt lgkmcnt(3)
	v_mfma_f32_16x16x32_bf16 v[110:113], v[196:199], v[164:167], v[110:113]
	s_waitcnt lgkmcnt(1)
	v_mfma_f32_16x16x32_bf16 v[106:109], v[204:207], v[164:167], v[106:109]
	v_mfma_f32_16x16x32_bf16 v[94:97], v[196:199], v[172:175], v[94:97]
	v_mfma_f32_16x16x32_bf16 v[90:93], v[204:207], v[172:175], v[90:93]
	v_mfma_f32_16x16x32_bf16 v[78:81], v[196:199], v[180:183], v[78:81]
	v_mfma_f32_16x16x32_bf16 v[74:77], v[204:207], v[180:183], v[74:77]
	v_mfma_f32_16x16x32_bf16 v[70:73], v[196:199], v[188:191], v[70:73]
	v_mfma_f32_16x16x32_bf16 v[66:69], v[204:207], v[188:191], v[66:69]
	v_mfma_f32_16x16x32_bf16 v[110:113], v[200:203], v[168:171], v[110:113]
	s_waitcnt lgkmcnt(0)
	v_mfma_f32_16x16x32_bf16 v[106:109], v[216:219], v[168:171], v[106:109]
	v_mfma_f32_16x16x32_bf16 v[94:97], v[200:203], v[176:179], v[94:97]
	v_mfma_f32_16x16x32_bf16 v[90:93], v[216:219], v[176:179], v[90:93]
	v_mfma_f32_16x16x32_bf16 v[78:81], v[200:203], v[184:187], v[78:81]
	v_mfma_f32_16x16x32_bf16 v[74:77], v[216:219], v[184:187], v[74:77]
	v_mfma_f32_16x16x32_bf16 v[70:73], v[200:203], v[192:195], v[70:73]
	v_mfma_f32_16x16x32_bf16 v[66:69], v[216:219], v[192:195], v[66:69]
	s_mov_b32 m0, s52
	s_barrier
	ds_read_b128 v[164:167], v141 offset:49152
	ds_read_b128 v[168:171], v141 offset:50176
	ds_read_b128 v[172:175], v141 offset:51200
	ds_read_b128 v[176:179], v141 offset:52224
	ds_read_b128 v[180:183], v141 offset:53248
	ds_read_b128 v[184:187], v141 offset:54272
	ds_read_b128 v[188:191], v141 offset:55296
	global_load_lds_dwordx4 v134, s[98:99]
	s_mov_b32 m0, s53
	ds_read_b128 v[192:195], v141 offset:56320
	global_load_lds_dwordx4 v132, s[98:99]
	s_barrier
	s_waitcnt lgkmcnt(7)
	v_mfma_f32_16x16x32_bf16 v[62:65], v[142:145], v[164:167], v[62:65]
	v_mfma_f32_16x16x32_bf16 v[58:61], v[156:159], v[164:167], v[58:61]
	s_waitcnt lgkmcnt(5)
	v_mfma_f32_16x16x32_bf16 v[54:57], v[142:145], v[172:175], v[54:57]
	v_mfma_f32_16x16x32_bf16 v[50:53], v[156:159], v[172:175], v[50:53]
	s_waitcnt lgkmcnt(3)
	v_mfma_f32_16x16x32_bf16 v[38:41], v[142:145], v[180:183], v[38:41]
	v_mfma_f32_16x16x32_bf16 v[34:37], v[156:159], v[180:183], v[34:37]
	s_waitcnt lgkmcnt(1)
	v_mfma_f32_16x16x32_bf16 v[22:25], v[142:145], v[188:191], v[22:25]
	v_mfma_f32_16x16x32_bf16 v[18:21], v[156:159], v[188:191], v[18:21]
	v_mfma_f32_16x16x32_bf16 v[62:65], v[152:155], v[168:171], v[62:65]
	v_mfma_f32_16x16x32_bf16 v[58:61], v[160:163], v[168:171], v[58:61]
	v_mfma_f32_16x16x32_bf16 v[54:57], v[152:155], v[176:179], v[54:57]
	v_mfma_f32_16x16x32_bf16 v[50:53], v[160:163], v[176:179], v[50:53]
	v_mfma_f32_16x16x32_bf16 v[38:41], v[152:155], v[184:187], v[38:41]
	v_mfma_f32_16x16x32_bf16 v[34:37], v[160:163], v[184:187], v[34:37]
	s_waitcnt lgkmcnt(0)
	v_mfma_f32_16x16x32_bf16 v[22:25], v[152:155], v[192:195], v[22:25]
	v_mfma_f32_16x16x32_bf16 v[18:21], v[160:163], v[192:195], v[18:21]
	s_barrier
	s_mov_b32 m0, s83
	s_add_u32 s36, s36, 0x80080
	s_addc_u32 s37, s37, 0
	global_load_lds_dwordx4 v0, s[36:37]
	s_add_i32 m0, s83, 0x2000
	s_nop 0
	global_load_lds_dwordx4 v130, s[36:37]
	s_waitcnt vmcnt(6)
	s_barrier
	v_mfma_f32_16x16x32_bf16 v[46:49], v[196:199], v[164:167], v[46:49]
	v_mfma_f32_16x16x32_bf16 v[42:45], v[204:207], v[164:167], v[42:45]
	v_mfma_f32_16x16x32_bf16 v[30:33], v[196:199], v[172:175], v[30:33]
	v_mfma_f32_16x16x32_bf16 v[26:29], v[204:207], v[172:175], v[26:29]
	v_mfma_f32_16x16x32_bf16 v[14:17], v[196:199], v[180:183], v[14:17]
	v_mfma_f32_16x16x32_bf16 v[10:13], v[204:207], v[180:183], v[10:13]
	v_mfma_f32_16x16x32_bf16 v[6:9], v[196:199], v[188:191], v[6:9]
	v_mfma_f32_16x16x32_bf16 v[2:5], v[204:207], v[188:191], v[2:5]
	v_mfma_f32_16x16x32_bf16 v[46:49], v[200:203], v[168:171], v[46:49]
	v_mfma_f32_16x16x32_bf16 v[42:45], v[216:219], v[168:171], v[42:45]
	v_mfma_f32_16x16x32_bf16 v[30:33], v[200:203], v[176:179], v[30:33]
	v_mfma_f32_16x16x32_bf16 v[26:29], v[216:219], v[176:179], v[26:29]
	v_mfma_f32_16x16x32_bf16 v[14:17], v[200:203], v[184:187], v[14:17]
	v_mfma_f32_16x16x32_bf16 v[10:13], v[216:219], v[184:187], v[10:13]
	v_mfma_f32_16x16x32_bf16 v[6:9], v[200:203], v[192:195], v[6:9]
	v_mfma_f32_16x16x32_bf16 v[2:5], v[216:219], v[192:195], v[2:5]
	s_add_i32 s68, s68, 2
	s_add_u32 s30, s30, 0x100
	s_addc_u32 s31, s31, 0
	s_add_u32 s43, s43, 0x100
	s_addc_u32 s67, s67, 0
	s_cmp_gt_u32 s68, 29
	s_barrier
	s_cbranch_scc0 .LBB0_939
	s_lshr_b32 s23, s66, 3
	s_mulk_i32 s23, 0x880
	s_lshl_b32 s30, s66, 8
	v_mov_b32_e32 v142, v148
	s_and_b32 s30, s30, 0x700
	s_add_i32 s23, s60, s23
	s_add_i32 s23, s23, s30
	v_and_or_b32 v144, v142, 15, s23
	s_lshl_b32 s23, s65, 8
	v_lshrrev_b32_e32 v142, 1, v142
	v_and_or_b32 v142, v142, 24, s23
	v_or_b32_e32 v142, s51, v142
	v_cvt_pk_bf16_f32 v126, v126, v127
	v_cvt_pk_bf16_f32 v127, v128, v129
	v_cvt_pk_bf16_f32 v128, v122, v123
	v_mov_b64_e32 v[122:123], s[6:7]
	v_ashrrev_i32_e32 v143, 31, v142
	v_cvt_pk_bf16_f32 v70, v70, v71
	v_cvt_pk_bf16_f32 v71, v72, v73
	v_cvt_pk_bf16_f32 v72, v66, v67
	v_add_u32_e32 v66, 0x80, v144
	v_cvt_pk_bf16_f32 v129, v124, v125
	v_mad_i64_i32 v[124:125], s[30:31], v144, s74, v[122:123]
	v_lshlrev_b64 v[142:143], 1, v[142:143]
	v_cvt_pk_bf16_f32 v62, v62, v63
	v_cvt_pk_bf16_f32 v63, v64, v65
	v_cvt_pk_bf16_f32 v64, v58, v59
	v_mad_i64_i32 v[58:59], s[30:31], v66, s74, v[122:123]
	v_lshl_add_u64 v[124:125], v[124:125], 0, v[142:143]
	v_cvt_pk_bf16_f32 v110, v110, v111
	v_cvt_pk_bf16_f32 v111, v112, v113
	v_cvt_pk_bf16_f32 v112, v106, v107
	v_cvt_pk_bf16_f32 v113, v108, v109
	v_lshl_add_u64 v[58:59], v[58:59], 0, v[142:143]
	v_cvt_pk_bf16_f32 v46, v46, v47
	v_cvt_pk_bf16_f32 v47, v48, v49
	v_cvt_pk_bf16_f32 v48, v42, v43
	v_cvt_pk_bf16_f32 v49, v44, v45
	global_store_dwordx4 v[124:125], v[110:113], off offset:256
	global_store_dwordx4 v[58:59], v[46:49], off offset:256
	v_cvt_pk_bf16_f32 v94, v94, v95
	v_add_u32_e32 v110, 16, v144
	v_add_u32_e32 v46, 0x90, v144
	v_mad_i64_i32 v[110:111], s[30:31], v110, s74, v[122:123]
	v_mad_i64_i32 v[46:47], s[30:31], v46, s74, v[122:123]
	v_lshl_add_u64 v[110:111], v[110:111], 0, v[142:143]
	v_cvt_pk_bf16_f32 v95, v96, v97
	v_cvt_pk_bf16_f32 v96, v90, v91
	v_cvt_pk_bf16_f32 v97, v92, v93
	v_lshl_add_u64 v[46:47], v[46:47], 0, v[142:143]
	v_cvt_pk_bf16_f32 v30, v30, v31
	v_cvt_pk_bf16_f32 v31, v32, v33
	v_cvt_pk_bf16_f32 v32, v26, v27
	v_cvt_pk_bf16_f32 v33, v28, v29
	global_store_dwordx4 v[110:111], v[94:97], off offset:256
	global_store_dwordx4 v[46:47], v[30:33], off offset:256
	v_cvt_pk_bf16_f32 v78, v78, v79
	v_add_u32_e32 v94, 32, v144
	v_add_u32_e32 v30, 0xa0, v144
	v_mad_i64_i32 v[94:95], s[30:31], v94, s74, v[122:123]
	v_mad_i64_i32 v[30:31], s[30:31], v30, s74, v[122:123]
	v_lshl_add_u64 v[94:95], v[94:95], 0, v[142:143]
	v_cvt_pk_bf16_f32 v79, v80, v81
	v_cvt_pk_bf16_f32 v80, v74, v75
	v_cvt_pk_bf16_f32 v81, v76, v77
	v_lshl_add_u64 v[30:31], v[30:31], 0, v[142:143]
	v_cvt_pk_bf16_f32 v14, v14, v15
	v_cvt_pk_bf16_f32 v15, v16, v17
	v_cvt_pk_bf16_f32 v16, v10, v11
	v_cvt_pk_bf16_f32 v17, v12, v13
	global_store_dwordx4 v[94:95], v[78:81], off offset:256
	global_store_dwordx4 v[30:31], v[14:17], off offset:256
	v_cvt_pk_bf16_f32 v106, v118, v119
	v_add_u32_e32 v78, 48, v144
	v_add_u32_e32 v14, 0xb0, v144
	v_mad_i64_i32 v[78:79], s[30:31], v78, s74, v[122:123]
	v_mad_i64_i32 v[14:15], s[30:31], v14, s74, v[122:123]
	v_cvt_pk_bf16_f32 v107, v120, v121
	v_cvt_pk_bf16_f32 v108, v114, v115
	v_cvt_pk_bf16_f32 v109, v116, v117
	v_cvt_pk_bf16_f32 v90, v102, v103
	v_cvt_pk_bf16_f32 v91, v104, v105
	v_cvt_pk_bf16_f32 v92, v98, v99
	v_cvt_pk_bf16_f32 v93, v100, v101
	v_cvt_pk_bf16_f32 v74, v86, v87
	v_cvt_pk_bf16_f32 v75, v88, v89
	v_cvt_pk_bf16_f32 v76, v82, v83
	v_cvt_pk_bf16_f32 v77, v84, v85
	v_lshl_add_u64 v[78:79], v[78:79], 0, v[142:143]
	v_cvt_pk_bf16_f32 v73, v68, v69
	v_cvt_pk_bf16_f32 v65, v60, v61
	v_cvt_pk_bf16_f32 v42, v54, v55
	v_cvt_pk_bf16_f32 v43, v56, v57
	v_cvt_pk_bf16_f32 v44, v50, v51
	v_cvt_pk_bf16_f32 v45, v52, v53
	v_cvt_pk_bf16_f32 v26, v38, v39
	v_cvt_pk_bf16_f32 v27, v40, v41
	v_cvt_pk_bf16_f32 v28, v34, v35
	v_cvt_pk_bf16_f32 v29, v36, v37
	v_cvt_pk_bf16_f32 v10, v22, v23
	v_cvt_pk_bf16_f32 v11, v24, v25
	v_cvt_pk_bf16_f32 v12, v18, v19
	v_cvt_pk_bf16_f32 v13, v20, v21
	v_lshl_add_u64 v[14:15], v[14:15], 0, v[142:143]
	v_cvt_pk_bf16_f32 v6, v6, v7
	v_cvt_pk_bf16_f32 v7, v8, v9
	v_cvt_pk_bf16_f32 v8, v2, v3
	v_cvt_pk_bf16_f32 v9, v4, v5
	s_and_b64 vcc, exec, s[0:1]
	s_mov_b32 s65, s22
	s_mov_b32 s66, s64
	s_mov_b64 s[36:37], s[28:29]
	s_mov_b64 s[30:31], s[26:27]
	global_store_dwordx4 v[124:125], v[126:129], off
	global_store_dwordx4 v[110:111], v[106:109], off
	global_store_dwordx4 v[94:95], v[90:93], off
	global_store_dwordx4 v[78:79], v[74:77], off
	global_store_dwordx4 v[78:79], v[70:73], off offset:256
	global_store_dwordx4 v[58:59], v[62:65], off
	global_store_dwordx4 v[46:47], v[42:45], off
	global_store_dwordx4 v[30:31], v[26:29], off
	global_store_dwordx4 v[14:15], v[10:13], off
	global_store_dwordx4 v[14:15], v[6:9], off offset:256
	s_cbranch_vccz .LBB0_934
	s_waitcnt vmcnt(0)
	s_cmpk_gt_u32 s14, 0xff
	s_cbranch_scc1 .LBB0_943
	s_barrier

.LBB0_1083:
	s_add_u32 s42, s22, 0x100
	s_addc_u32 s43, s23, 0
	s_add_u32 s22, s6, 0x158080
	s_addc_u32 s23, s7, 0
	v_lshl_add_u64 v[142:143], s[22:23], 0, v[138:139]
	v_lshl_add_u64 v[144:145], s[22:23], 0, v[140:141]
	s_mov_b32 s78, -2
	s_mov_b64 s[22:23], 0
	v_add_u32_e32 v224, 0x10000, v146
	v_add_u32_e32 v225, 0x14000, v146
	v_add_u32_e32 v226, 0x18000, v146
	v_add_u32_e32 v227, 0x1c000, v146
	s_add_i32 s32, s52, 0x10000
	s_add_i32 s70, s52, 0x14000
	s_add_i32 s87, s52, 0x18000
	s_add_i32 s88, s52, 0x1c000
.LBB0_1084:
	s_add_u32 s30, s6, s22
	s_addc_u32 s31, s7, s23
	s_add_u32 s30, s30, 0x100
	s_addc_u32 s31, s31, 0
	s_add_u32 s79, s42, s22
	s_addc_u32 s80, s43, s23
	ds_read_b128 v[152:155], v224
	ds_read_b128 v[156:159], v224 offset:1024
	ds_read_b128 v[160:163], v224 offset:2048
	ds_read_b128 v[164:167], v224 offset:3072
	s_cmpk_eq_i32 s22, 0x2a00
	s_cselect_b32 s41, s13, s31
	s_cselect_b32 s40, s12, s30
	s_cselect_b32 s31, s9, s80
	s_cselect_b32 s30, s8, s79
	v_lshl_add_u64 v[200:201], v[142:143], 0, s[22:23]
	s_add_i32 m0, s53, 0xc000
	ds_read_b128 v[168:171], v147
	ds_read_b128 v[172:175], v147 offset:1024
	ds_read_b128 v[176:179], v147 offset:2048
	ds_read_b128 v[180:183], v147 offset:3072
	ds_read_b128 v[184:187], v147 offset:4096
	ds_read_b128 v[188:191], v147 offset:5120
	ds_read_b128 v[192:195], v147 offset:6144
	ds_read_b128 v[196:199], v147 offset:7168
	global_load_lds_dwordx4 v[200:201], off
	v_lshl_add_u64 v[200:201], v[144:145], 0, s[22:23]
	s_add_i32 m0, s53, 0xe000
	s_nop 0
	global_load_lds_dwordx4 v[200:201], off
	s_waitcnt lgkmcnt(8)
	s_barrier
	s_waitcnt lgkmcnt(7)
	v_mfma_f32_16x16x32_bf16 v[126:129], v[152:155], v[168:171], v[126:129]
	v_mfma_f32_16x16x32_bf16 v[122:125], v[160:163], v[168:171], v[122:125]
	s_waitcnt lgkmcnt(5)
	v_mfma_f32_16x16x32_bf16 v[110:113], v[152:155], v[176:179], v[110:113]
	v_mfma_f32_16x16x32_bf16 v[106:109], v[160:163], v[176:179], v[106:109]
	s_waitcnt lgkmcnt(3)
	v_mfma_f32_16x16x32_bf16 v[94:97], v[152:155], v[184:187], v[94:97]
	v_mfma_f32_16x16x32_bf16 v[90:93], v[160:163], v[184:187], v[90:93]
	s_waitcnt lgkmcnt(1)
	v_mfma_f32_16x16x32_bf16 v[78:81], v[152:155], v[192:195], v[78:81]
	v_mfma_f32_16x16x32_bf16 v[74:77], v[160:163], v[192:195], v[74:77]
	v_mfma_f32_16x16x32_bf16 v[126:129], v[156:159], v[172:175], v[126:129]
	v_mfma_f32_16x16x32_bf16 v[122:125], v[164:167], v[172:175], v[122:125]
	v_mfma_f32_16x16x32_bf16 v[110:113], v[156:159], v[180:183], v[110:113]
	v_mfma_f32_16x16x32_bf16 v[106:109], v[164:167], v[180:183], v[106:109]
	v_mfma_f32_16x16x32_bf16 v[94:97], v[156:159], v[188:191], v[94:97]
	v_mfma_f32_16x16x32_bf16 v[90:93], v[164:167], v[188:191], v[90:93]
	s_waitcnt lgkmcnt(0)
	v_mfma_f32_16x16x32_bf16 v[78:81], v[156:159], v[196:199], v[78:81]
	v_mfma_f32_16x16x32_bf16 v[74:77], v[164:167], v[196:199], v[74:77]
	s_barrier
	s_mov_b32 m0, s32
	ds_read_b128 v[200:203], v225
	ds_read_b128 v[204:207], v225 offset:1024
	ds_read_b128 v[216:219], v225 offset:2048
	global_load_lds_dwordx4 v0, s[30:31]
	s_add_i32 m0, s32, 0x2000
	ds_read_b128 v[220:223], v225 offset:3072
	global_load_lds_dwordx4 v136, s[30:31]
	s_barrier
	s_waitcnt lgkmcnt(3)
	v_mfma_f32_16x16x32_bf16 v[118:121], v[200:203], v[168:171], v[118:121]
	s_waitcnt lgkmcnt(1)
	v_mfma_f32_16x16x32_bf16 v[114:117], v[216:219], v[168:171], v[114:117]
	v_mfma_f32_16x16x32_bf16 v[102:105], v[200:203], v[176:179], v[102:105]
	v_mfma_f32_16x16x32_bf16 v[98:101], v[216:219], v[176:179], v[98:101]
	v_mfma_f32_16x16x32_bf16 v[86:89], v[200:203], v[184:187], v[86:89]
	v_mfma_f32_16x16x32_bf16 v[82:85], v[216:219], v[184:187], v[82:85]
	v_mfma_f32_16x16x32_bf16 v[70:73], v[200:203], v[192:195], v[70:73]
	v_mfma_f32_16x16x32_bf16 v[66:69], v[216:219], v[192:195], v[66:69]
	v_mfma_f32_16x16x32_bf16 v[118:121], v[204:207], v[172:175], v[118:121]
	s_waitcnt lgkmcnt(0)
	v_mfma_f32_16x16x32_bf16 v[114:117], v[220:223], v[172:175], v[114:117]
	v_mfma_f32_16x16x32_bf16 v[102:105], v[204:207], v[180:183], v[102:105]
	v_mfma_f32_16x16x32_bf16 v[98:101], v[220:223], v[180:183], v[98:101]
	v_mfma_f32_16x16x32_bf16 v[86:89], v[204:207], v[188:191], v[86:89]
	v_mfma_f32_16x16x32_bf16 v[82:85], v[220:223], v[188:191], v[82:85]
	v_mfma_f32_16x16x32_bf16 v[70:73], v[204:207], v[196:199], v[70:73]
	v_mfma_f32_16x16x32_bf16 v[66:69], v[220:223], v[196:199], v[66:69]
	s_mov_b32 m0, s53
	s_add_u32 s98, s40, 0x80
	s_addc_u32 s99, s41, 0
	s_barrier
	ds_read_b128 v[168:171], v147 offset:16384
	ds_read_b128 v[172:175], v147 offset:17408
	ds_read_b128 v[176:179], v147 offset:18432
	ds_read_b128 v[180:183], v147 offset:19456
	ds_read_b128 v[184:187], v147 offset:20480
	ds_read_b128 v[188:191], v147 offset:21504
	ds_read_b128 v[192:195], v147 offset:22528
	global_load_lds_dwordx4 v0, s[40:41]
	s_mov_b32 m0, s60
	ds_read_b128 v[196:199], v147 offset:23552
	global_load_lds_dwordx4 v136, s[40:41]
	s_barrier
	s_waitcnt lgkmcnt(7)
	v_mfma_f32_16x16x32_bf16 v[62:65], v[152:155], v[168:171], v[62:65]
	v_mfma_f32_16x16x32_bf16 v[58:61], v[160:163], v[168:171], v[58:61]
	s_waitcnt lgkmcnt(5)
	v_mfma_f32_16x16x32_bf16 v[46:49], v[152:155], v[176:179], v[46:49]
	v_mfma_f32_16x16x32_bf16 v[42:45], v[160:163], v[176:179], v[42:45]
	s_waitcnt lgkmcnt(3)
	v_mfma_f32_16x16x32_bf16 v[30:33], v[152:155], v[184:187], v[30:33]
	v_mfma_f32_16x16x32_bf16 v[26:29], v[160:163], v[184:187], v[26:29]
	s_waitcnt lgkmcnt(1)
	v_mfma_f32_16x16x32_bf16 v[14:17], v[152:155], v[192:195], v[14:17]
	v_mfma_f32_16x16x32_bf16 v[10:13], v[160:163], v[192:195], v[10:13]
	v_mfma_f32_16x16x32_bf16 v[62:65], v[156:159], v[172:175], v[62:65]
	v_mfma_f32_16x16x32_bf16 v[58:61], v[164:167], v[172:175], v[58:61]
	v_mfma_f32_16x16x32_bf16 v[46:49], v[156:159], v[180:183], v[46:49]
	v_mfma_f32_16x16x32_bf16 v[42:45], v[164:167], v[180:183], v[42:45]
	v_mfma_f32_16x16x32_bf16 v[30:33], v[156:159], v[188:191], v[30:33]
	v_mfma_f32_16x16x32_bf16 v[26:29], v[164:167], v[188:191], v[26:29]
	s_waitcnt lgkmcnt(0)
	v_mfma_f32_16x16x32_bf16 v[14:17], v[156:159], v[196:199], v[14:17]
	v_mfma_f32_16x16x32_bf16 v[10:13], v[164:167], v[196:199], v[10:13]
	s_barrier
	s_mov_b32 m0, s70
	s_add_u32 s80, s30, 0x158000
	s_addc_u32 s81, s31, 0
	global_load_lds_dwordx4 v0, s[80:81]
	s_add_i32 m0, s70, 0x2000
	s_nop 0
	global_load_lds_dwordx4 v136, s[80:81]
	s_waitcnt vmcnt(6)
	s_barrier
	v_mfma_f32_16x16x32_bf16 v[54:57], v[200:203], v[168:171], v[54:57]
	v_mfma_f32_16x16x32_bf16 v[50:53], v[216:219], v[168:171], v[50:53]
	v_mfma_f32_16x16x32_bf16 v[38:41], v[200:203], v[176:179], v[38:41]
	v_mfma_f32_16x16x32_bf16 v[34:37], v[216:219], v[176:179], v[34:37]
	v_mfma_f32_16x16x32_bf16 v[22:25], v[200:203], v[184:187], v[22:25]
	v_mfma_f32_16x16x32_bf16 v[18:21], v[216:219], v[184:187], v[18:21]
	v_mfma_f32_16x16x32_bf16 v[6:9], v[200:203], v[192:195], v[6:9]
	v_mfma_f32_16x16x32_bf16 v[2:5], v[216:219], v[192:195], v[2:5]
	v_mfma_f32_16x16x32_bf16 v[54:57], v[204:207], v[172:175], v[54:57]
	v_mfma_f32_16x16x32_bf16 v[50:53], v[220:223], v[172:175], v[50:53]
	v_mfma_f32_16x16x32_bf16 v[38:41], v[204:207], v[180:183], v[38:41]
	v_mfma_f32_16x16x32_bf16 v[34:37], v[220:223], v[180:183], v[34:37]
	v_mfma_f32_16x16x32_bf16 v[22:25], v[204:207], v[188:191], v[22:25]
	v_mfma_f32_16x16x32_bf16 v[18:21], v[220:223], v[188:191], v[18:21]
	v_mfma_f32_16x16x32_bf16 v[6:9], v[204:207], v[196:199], v[6:9]
	v_mfma_f32_16x16x32_bf16 v[2:5], v[220:223], v[196:199], v[2:5]
	s_barrier
	ds_read_b128 v[152:155], v226
	ds_read_b128 v[156:159], v226 offset:1024
	ds_read_b128 v[160:163], v226 offset:2048
	ds_read_b128 v[164:167], v226 offset:3072
	s_add_u32 s40, s40, 0x158000
	s_addc_u32 s41, s41, 0
	s_mov_b32 m0, s65
	ds_read_b128 v[168:171], v147 offset:32768
	ds_read_b128 v[172:175], v147 offset:33792
	ds_read_b128 v[176:179], v147 offset:34816
	ds_read_b128 v[180:183], v147 offset:35840
	ds_read_b128 v[184:187], v147 offset:36864
	ds_read_b128 v[188:191], v147 offset:37888
	ds_read_b128 v[192:195], v147 offset:38912
	global_load_lds_dwordx4 v0, s[40:41]
	s_mov_b32 m0, s66
	ds_read_b128 v[196:199], v147 offset:39936
	global_load_lds_dwordx4 v136, s[40:41]
	s_waitcnt lgkmcnt(8)
	s_barrier
	s_waitcnt lgkmcnt(7)
	v_mfma_f32_16x16x32_bf16 v[126:129], v[152:155], v[168:171], v[126:129]
	v_mfma_f32_16x16x32_bf16 v[122:125], v[160:163], v[168:171], v[122:125]
	s_waitcnt lgkmcnt(5)
	v_mfma_f32_16x16x32_bf16 v[110:113], v[152:155], v[176:179], v[110:113]
	v_mfma_f32_16x16x32_bf16 v[106:109], v[160:163], v[176:179], v[106:109]
	s_waitcnt lgkmcnt(3)
	v_mfma_f32_16x16x32_bf16 v[94:97], v[152:155], v[184:187], v[94:97]
	v_mfma_f32_16x16x32_bf16 v[90:93], v[160:163], v[184:187], v[90:93]
	s_waitcnt lgkmcnt(1)
	v_mfma_f32_16x16x32_bf16 v[78:81], v[152:155], v[192:195], v[78:81]
	v_mfma_f32_16x16x32_bf16 v[74:77], v[160:163], v[192:195], v[74:77]
	v_mfma_f32_16x16x32_bf16 v[126:129], v[156:159], v[172:175], v[126:129]
	v_mfma_f32_16x16x32_bf16 v[122:125], v[164:167], v[172:175], v[122:125]
	v_mfma_f32_16x16x32_bf16 v[110:113], v[156:159], v[180:183], v[110:113]
	v_mfma_f32_16x16x32_bf16 v[106:109], v[164:167], v[180:183], v[106:109]
	v_mfma_f32_16x16x32_bf16 v[94:97], v[156:159], v[188:191], v[94:97]
	v_mfma_f32_16x16x32_bf16 v[90:93], v[164:167], v[188:191], v[90:93]
	s_waitcnt lgkmcnt(0)
	v_mfma_f32_16x16x32_bf16 v[78:81], v[156:159], v[196:199], v[78:81]
	v_mfma_f32_16x16x32_bf16 v[74:77], v[164:167], v[196:199], v[74:77]
	s_barrier
	s_add_u32 s100, s30, 0x80
	s_addc_u32 s101, s31, 0
	s_mov_b32 m0, s87
	ds_read_b128 v[200:203], v227
	ds_read_b128 v[204:207], v227 offset:1024
	ds_read_b128 v[216:219], v227 offset:2048
	global_load_lds_dwordx4 v0, s[100:101]
	s_add_i32 m0, s87, 0x2000
	ds_read_b128 v[220:223], v227 offset:3072
	global_load_lds_dwordx4 v136, s[100:101]
	s_barrier
	s_waitcnt lgkmcnt(3)
	v_mfma_f32_16x16x32_bf16 v[118:121], v[200:203], v[168:171], v[118:121]
	s_waitcnt lgkmcnt(1)
	v_mfma_f32_16x16x32_bf16 v[114:117], v[216:219], v[168:171], v[114:117]
	v_mfma_f32_16x16x32_bf16 v[102:105], v[200:203], v[176:179], v[102:105]
	v_mfma_f32_16x16x32_bf16 v[98:101], v[216:219], v[176:179], v[98:101]
	v_mfma_f32_16x16x32_bf16 v[86:89], v[200:203], v[184:187], v[86:89]
	v_mfma_f32_16x16x32_bf16 v[82:85], v[216:219], v[184:187], v[82:85]
	v_mfma_f32_16x16x32_bf16 v[70:73], v[200:203], v[192:195], v[70:73]
	v_mfma_f32_16x16x32_bf16 v[66:69], v[216:219], v[192:195], v[66:69]
	v_mfma_f32_16x16x32_bf16 v[118:121], v[204:207], v[172:175], v[118:121]
	s_waitcnt lgkmcnt(0)
	v_mfma_f32_16x16x32_bf16 v[114:117], v[220:223], v[172:175], v[114:117]
	v_mfma_f32_16x16x32_bf16 v[102:105], v[204:207], v[180:183], v[102:105]
	v_mfma_f32_16x16x32_bf16 v[98:101], v[220:223], v[180:183], v[98:101]
	v_mfma_f32_16x16x32_bf16 v[86:89], v[204:207], v[188:191], v[86:89]
	v_mfma_f32_16x16x32_bf16 v[82:85], v[220:223], v[188:191], v[82:85]
	v_mfma_f32_16x16x32_bf16 v[70:73], v[204:207], v[196:199], v[70:73]
	v_mfma_f32_16x16x32_bf16 v[66:69], v[220:223], v[196:199], v[66:69]
	s_mov_b32 m0, s67
	s_barrier
	ds_read_b128 v[168:171], v147 offset:49152
	ds_read_b128 v[172:175], v147 offset:50176
	ds_read_b128 v[176:179], v147 offset:51200
	ds_read_b128 v[180:183], v147 offset:52224
	ds_read_b128 v[184:187], v147 offset:53248
	ds_read_b128 v[188:191], v147 offset:54272
	ds_read_b128 v[192:195], v147 offset:55296
	global_load_lds_dwordx4 v0, s[98:99]
	s_mov_b32 m0, s68
	ds_read_b128 v[196:199], v147 offset:56320
	global_load_lds_dwordx4 v136, s[98:99]
	s_barrier
	s_waitcnt lgkmcnt(7)
	v_mfma_f32_16x16x32_bf16 v[62:65], v[152:155], v[168:171], v[62:65]
	v_mfma_f32_16x16x32_bf16 v[58:61], v[160:163], v[168:171], v[58:61]
	s_waitcnt lgkmcnt(5)
	v_mfma_f32_16x16x32_bf16 v[46:49], v[152:155], v[176:179], v[46:49]
	v_mfma_f32_16x16x32_bf16 v[42:45], v[160:163], v[176:179], v[42:45]
	s_waitcnt lgkmcnt(3)
	v_mfma_f32_16x16x32_bf16 v[30:33], v[152:155], v[184:187], v[30:33]
	v_mfma_f32_16x16x32_bf16 v[26:29], v[160:163], v[184:187], v[26:29]
	s_waitcnt lgkmcnt(1)
	v_mfma_f32_16x16x32_bf16 v[14:17], v[152:155], v[192:195], v[14:17]
	v_mfma_f32_16x16x32_bf16 v[10:13], v[160:163], v[192:195], v[10:13]
	v_mfma_f32_16x16x32_bf16 v[62:65], v[156:159], v[172:175], v[62:65]
	v_mfma_f32_16x16x32_bf16 v[58:61], v[164:167], v[172:175], v[58:61]
	v_mfma_f32_16x16x32_bf16 v[46:49], v[156:159], v[180:183], v[46:49]
	v_mfma_f32_16x16x32_bf16 v[42:45], v[164:167], v[180:183], v[42:45]
	v_mfma_f32_16x16x32_bf16 v[30:33], v[156:159], v[188:191], v[30:33]
	v_mfma_f32_16x16x32_bf16 v[26:29], v[164:167], v[188:191], v[26:29]
	s_waitcnt lgkmcnt(0)
	v_mfma_f32_16x16x32_bf16 v[14:17], v[156:159], v[196:199], v[14:17]
	v_mfma_f32_16x16x32_bf16 v[10:13], v[164:167], v[196:199], v[10:13]
	s_barrier
	s_mov_b32 m0, s88
	s_add_u32 s30, s30, 0x158080
	s_addc_u32 s31, s31, 0
	global_load_lds_dwordx4 v0, s[30:31]
	s_add_i32 m0, s88, 0x2000
	s_nop 0
	global_load_lds_dwordx4 v136, s[30:31]
	s_waitcnt vmcnt(6)
	s_barrier
	v_mfma_f32_16x16x32_bf16 v[54:57], v[200:203], v[168:171], v[54:57]
	v_mfma_f32_16x16x32_bf16 v[50:53], v[216:219], v[168:171], v[50:53]
	v_mfma_f32_16x16x32_bf16 v[38:41], v[200:203], v[176:179], v[38:41]
	v_mfma_f32_16x16x32_bf16 v[34:37], v[216:219], v[176:179], v[34:37]
	v_mfma_f32_16x16x32_bf16 v[22:25], v[200:203], v[184:187], v[22:25]
	v_mfma_f32_16x16x32_bf16 v[18:21], v[216:219], v[184:187], v[18:21]
	v_mfma_f32_16x16x32_bf16 v[6:9], v[200:203], v[192:195], v[6:9]
	v_mfma_f32_16x16x32_bf16 v[2:5], v[216:219], v[192:195], v[2:5]
	v_mfma_f32_16x16x32_bf16 v[54:57], v[204:207], v[172:175], v[54:57]
	v_mfma_f32_16x16x32_bf16 v[50:53], v[220:223], v[172:175], v[50:53]
	v_mfma_f32_16x16x32_bf16 v[38:41], v[204:207], v[180:183], v[38:41]
	v_mfma_f32_16x16x32_bf16 v[34:37], v[220:223], v[180:183], v[34:37]
	v_mfma_f32_16x16x32_bf16 v[22:25], v[204:207], v[188:191], v[22:25]
	v_mfma_f32_16x16x32_bf16 v[18:21], v[220:223], v[188:191], v[18:21]
	v_mfma_f32_16x16x32_bf16 v[6:9], v[204:207], v[196:199], v[6:9]
	v_mfma_f32_16x16x32_bf16 v[2:5], v[220:223], v[196:199], v[2:5]
	s_add_i32 s78, s78, 2
	s_add_u32 s22, s22, 0x100
	s_addc_u32 s23, s23, 0
	s_cmpk_gt_u32 s78, 0x53
	s_barrier
	s_cbranch_scc0 .LBB0_1084
	s_add_u32 s22, s42, 0xffffff00
	s_addc_u32 s23, s43, -1
	s_and_b64 vcc, exec, s[38:39]
	s_cbranch_vccnz .LBB0_1071
	v_mov_b32_e32 v2, 0
	s_mov_b32 s14, s75
	s_mov_b32 s50, s76
	s_mov_b64 s[6:7], s[12:13]
	s_mov_b32 s69, s77
	v_mov_b32_e32 v3, v2
	v_mov_b32_e32 v4, v2
	v_mov_b32_e32 v5, v2
	v_mov_b32_e32 v6, v2
	v_mov_b32_e32 v7, v2
	v_mov_b32_e32 v8, v2
	v_mov_b32_e32 v9, v2
	v_mov_b32_e32 v18, v2
	v_mov_b32_e32 v19, v2
	v_mov_b32_e32 v20, v2
	v_mov_b32_e32 v21, v2
	v_mov_b32_e32 v22, v2
	v_mov_b32_e32 v23, v2
	v_mov_b32_e32 v24, v2
	v_mov_b32_e32 v25, v2
	v_mov_b32_e32 v34, v2
	v_mov_b32_e32 v35, v2
	v_mov_b32_e32 v36, v2
	v_mov_b32_e32 v37, v2
	v_mov_b32_e32 v38, v2
	v_mov_b32_e32 v39, v2
	v_mov_b32_e32 v40, v2
	v_mov_b32_e32 v41, v2
	v_mov_b32_e32 v50, v2
	v_mov_b32_e32 v51, v2
	v_mov_b32_e32 v52, v2
	v_mov_b32_e32 v53, v2
	v_mov_b32_e32 v54, v2
	v_mov_b32_e32 v55, v2
	v_mov_b32_e32 v56, v2
	v_mov_b32_e32 v57, v2
	v_mov_b32_e32 v10, v2
	v_mov_b32_e32 v11, v2
	v_mov_b32_e32 v12, v2
	v_mov_b32_e32 v13, v2
	v_mov_b32_e32 v14, v2
	v_mov_b32_e32 v15, v2
	v_mov_b32_e32 v16, v2
	v_mov_b32_e32 v17, v2
	v_mov_b32_e32 v26, v2
	v_mov_b32_e32 v27, v2
	v_mov_b32_e32 v28, v2
	v_mov_b32_e32 v29, v2
	v_mov_b32_e32 v30, v2
	v_mov_b32_e32 v31, v2
	v_mov_b32_e32 v32, v2
	v_mov_b32_e32 v33, v2
	v_mov_b32_e32 v42, v2
	v_mov_b32_e32 v43, v2
	v_mov_b32_e32 v44, v2
	v_mov_b32_e32 v45, v2
	v_mov_b32_e32 v46, v2
	v_mov_b32_e32 v47, v2
	v_mov_b32_e32 v48, v2
	v_mov_b32_e32 v49, v2
	v_mov_b32_e32 v58, v2
	v_mov_b32_e32 v59, v2
	v_mov_b32_e32 v60, v2
	v_mov_b32_e32 v61, v2
	v_mov_b32_e32 v62, v2
	v_mov_b32_e32 v63, v2
	v_mov_b32_e32 v64, v2
	v_mov_b32_e32 v65, v2
	v_mov_b32_e32 v66, v2
	v_mov_b32_e32 v67, v2
	v_mov_b32_e32 v68, v2
	v_mov_b32_e32 v69, v2
	v_mov_b32_e32 v70, v2
	v_mov_b32_e32 v71, v2
	v_mov_b32_e32 v72, v2
	v_mov_b32_e32 v73, v2
	v_mov_b32_e32 v82, v2
	v_mov_b32_e32 v83, v2
	v_mov_b32_e32 v84, v2
	v_mov_b32_e32 v85, v2
	v_mov_b32_e32 v86, v2
	v_mov_b32_e32 v87, v2
	v_mov_b32_e32 v88, v2
	v_mov_b32_e32 v89, v2
	v_mov_b32_e32 v98, v2
	v_mov_b32_e32 v99, v2
	v_mov_b32_e32 v100, v2
	v_mov_b32_e32 v101, v2
	v_mov_b32_e32 v102, v2
	v_mov_b32_e32 v103, v2
	v_mov_b32_e32 v104, v2
	v_mov_b32_e32 v105, v2
	v_mov_b32_e32 v114, v2
	v_mov_b32_e32 v115, v2
	v_mov_b32_e32 v116, v2
	v_mov_b32_e32 v117, v2
	v_mov_b32_e32 v118, v2
	v_mov_b32_e32 v119, v2
	v_mov_b32_e32 v120, v2
	v_mov_b32_e32 v121, v2
	v_mov_b32_e32 v74, v2
	v_mov_b32_e32 v75, v2
	v_mov_b32_e32 v76, v2
	v_mov_b32_e32 v77, v2
	v_mov_b32_e32 v78, v2
	v_mov_b32_e32 v79, v2
	v_mov_b32_e32 v80, v2
	v_mov_b32_e32 v81, v2
	v_mov_b32_e32 v90, v2
	v_mov_b32_e32 v91, v2
	v_mov_b32_e32 v92, v2
	v_mov_b32_e32 v93, v2
	v_mov_b32_e32 v94, v2
	v_mov_b32_e32 v95, v2
	v_mov_b32_e32 v96, v2
	v_mov_b32_e32 v97, v2
	v_mov_b32_e32 v106, v2
	v_mov_b32_e32 v107, v2
	v_mov_b32_e32 v108, v2
	v_mov_b32_e32 v109, v2
	v_mov_b32_e32 v110, v2
	v_mov_b32_e32 v111, v2
	v_mov_b32_e32 v112, v2
	v_mov_b32_e32 v113, v2
	v_mov_b32_e32 v122, v2
	v_mov_b32_e32 v123, v2
	v_mov_b32_e32 v124, v2
	v_mov_b32_e32 v125, v2
	v_mov_b32_e32 v126, v2
	v_mov_b32_e32 v127, v2
	v_mov_b32_e32 v128, v2
	v_mov_b32_e32 v129, v2
	s_andn2_b64 vcc, exec, s[0:1]
	s_cbranch_vccnz .LBB0_1072
